# K-loop back edge: counter/pointer SALU block moved from behind the loop-back barrier into the last MFMA burst (8 loops)
# baseline (speedup 1.0000x reference)
.LBB0_197:
	ds_read_b128 v[104:107], v171
	ds_read_b128 v[108:111], v171 offset:1024
	ds_read_b128 v[120:123], v171 offset:2048
	ds_read_b128 v[124:127], v171 offset:3072
	ds_read_b128 v[160:163], v172
	ds_read_b128 v[176:179], v172 offset:1024
	ds_read_b128 v[180:183], v172 offset:2048
	ds_read_b128 v[184:187], v172 offset:3072
	s_add_u32 s54, s52, 0xfffc0080
	s_addc_u32 s55, s53, -1
	s_cmp_eq_u32 s88, 12
	s_cselect_b32 s57, s9, s55
	s_cselect_b32 s56, s45, s54
	s_cselect_b32 s55, s43, s87
	s_cselect_b32 s54, s51, s86
	v_lshl_add_u64 v[164:165], s[52:53], 0, v[152:153]
	s_add_i32 m0, s64, 0xc000
	ds_read_b128 v[188:191], v173
	ds_read_b128 v[192:195], v173 offset:1024
	ds_read_b128 v[196:199], v173 offset:2048
	ds_read_b128 v[200:203], v173 offset:3072
	ds_read_b128 v[204:207], v173 offset:4096
	ds_read_b128 v[212:215], v173 offset:5120
	ds_read_b128 v[216:219], v173 offset:6144
	ds_read_b128 v[220:223], v173 offset:7168
	global_load_lds_dwordx4 v[164:165], off
	v_lshl_add_u64 v[164:165], s[52:53], 0, v[154:155]
	s_add_i32 m0, s64, 0xe000
	s_nop 0
	global_load_lds_dwordx4 v[164:165], off
	s_waitcnt vmcnt(8)
	s_waitcnt lgkmcnt(0)
	s_setprio 1
	s_barrier
	v_mfma_f32_16x16x32_bf16 v[140:143], v[104:107], v[188:191], v[140:143]
	v_mfma_f32_16x16x32_bf16 v[136:139], v[120:123], v[188:191], v[136:139]
	v_mfma_f32_16x16x32_bf16 v[116:119], v[104:107], v[196:199], v[116:119]
	v_mfma_f32_16x16x32_bf16 v[112:115], v[120:123], v[196:199], v[112:115]
	v_mfma_f32_16x16x32_bf16 v[92:95], v[104:107], v[204:207], v[92:95]
	v_mfma_f32_16x16x32_bf16 v[88:91], v[120:123], v[204:207], v[88:91]
	v_mfma_f32_16x16x32_bf16 v[76:79], v[104:107], v[216:219], v[76:79]
	v_mfma_f32_16x16x32_bf16 v[72:75], v[120:123], v[216:219], v[72:75]
	v_mfma_f32_16x16x32_bf16 v[140:143], v[108:111], v[192:195], v[140:143]
	v_mfma_f32_16x16x32_bf16 v[136:139], v[124:127], v[192:195], v[136:139]
	v_mfma_f32_16x16x32_bf16 v[116:119], v[108:111], v[200:203], v[116:119]
	v_mfma_f32_16x16x32_bf16 v[112:115], v[124:127], v[200:203], v[112:115]
	v_mfma_f32_16x16x32_bf16 v[92:95], v[108:111], v[212:215], v[92:95]
	v_mfma_f32_16x16x32_bf16 v[88:91], v[124:127], v[212:215], v[88:91]
	v_mfma_f32_16x16x32_bf16 v[76:79], v[108:111], v[220:223], v[76:79]
	v_mfma_f32_16x16x32_bf16 v[72:75], v[124:127], v[220:223], v[72:75]
	s_setprio 0
	s_setprio 1
	v_mfma_f32_16x16x32_bf16 v[132:135], v[160:163], v[188:191], v[132:135]
	v_mfma_f32_16x16x32_bf16 v[128:131], v[180:183], v[188:191], v[128:131]
	v_mfma_f32_16x16x32_bf16 v[100:103], v[160:163], v[196:199], v[100:103]
	v_mfma_f32_16x16x32_bf16 v[96:99], v[180:183], v[196:199], v[96:99]
	v_mfma_f32_16x16x32_bf16 v[84:87], v[160:163], v[204:207], v[84:87]
	v_mfma_f32_16x16x32_bf16 v[80:83], v[180:183], v[204:207], v[80:83]
	v_mfma_f32_16x16x32_bf16 v[68:71], v[160:163], v[216:219], v[68:71]
	v_mfma_f32_16x16x32_bf16 v[64:67], v[180:183], v[216:219], v[64:67]
	v_mfma_f32_16x16x32_bf16 v[132:135], v[176:179], v[192:195], v[132:135]
	v_mfma_f32_16x16x32_bf16 v[128:131], v[184:187], v[192:195], v[128:131]
	v_mfma_f32_16x16x32_bf16 v[100:103], v[176:179], v[200:203], v[100:103]
	v_mfma_f32_16x16x32_bf16 v[96:99], v[184:187], v[200:203], v[96:99]
	v_mfma_f32_16x16x32_bf16 v[84:87], v[176:179], v[212:215], v[84:87]
	v_mfma_f32_16x16x32_bf16 v[80:83], v[184:187], v[212:215], v[80:83]
	v_mfma_f32_16x16x32_bf16 v[68:71], v[176:179], v[220:223], v[68:71]
	v_mfma_f32_16x16x32_bf16 v[64:67], v[184:187], v[220:223], v[64:67]
	s_setprio 0
	s_barrier
	s_add_i32 s91, s80, s58
	v_lshl_add_u64 v[164:165], s[54:55], 0, v[146:147]
	s_mov_b32 m0, s91
	ds_read_b128 v[188:191], v173 offset:16384
	ds_read_b128 v[192:195], v173 offset:17408
	ds_read_b128 v[196:199], v173 offset:18432
	ds_read_b128 v[200:203], v173 offset:19456
	ds_read_b128 v[204:207], v173 offset:20480
	ds_read_b128 v[212:215], v173 offset:21504
	ds_read_b128 v[216:219], v173 offset:22528
	ds_read_b128 v[220:223], v173 offset:23552
	global_load_lds_dwordx4 v[164:165], off
	s_add_i32 m0, s91, 0x2000
	s_add_u32 s94, s54, 0x40000
	v_lshl_add_u64 v[224:225], s[54:55], 0, v[150:151]
	s_addc_u32 s95, s55, 0
	s_add_i32 s91, s81, s58
	global_load_lds_dwordx4 v[224:225], off
	v_lshl_add_u64 v[226:227], s[94:95], 0, v[146:147]
	s_mov_b32 m0, s91
	v_lshl_add_u64 v[228:229], s[56:57], 0, v[148:149]
	global_load_lds_dwordx4 v[226:227], off
	v_lshl_add_u64 v[226:227], s[94:95], 0, v[150:151]
	s_add_i32 m0, s91, 0x2000
	s_nop 0
	global_load_lds_dwordx4 v[226:227], off
	v_lshl_add_u64 v[226:227], s[56:57], 0, v[144:145]
	s_mov_b32 m0, s64
	s_nop 0
	global_load_lds_dwordx4 v[226:227], off
	s_mov_b32 m0, s65
	s_nop 0
	global_load_lds_dwordx4 v[228:229], off
	s_waitcnt vmcnt(8)
	s_waitcnt lgkmcnt(0)
	s_setprio 1
	s_barrier
	v_mfma_f32_16x16x32_bf16 v[60:63], v[104:107], v[188:191], v[60:63]
	v_mfma_f32_16x16x32_bf16 v[56:59], v[120:123], v[188:191], v[56:59]
	v_mfma_f32_16x16x32_bf16 v[44:47], v[104:107], v[196:199], v[44:47]
	v_mfma_f32_16x16x32_bf16 v[40:43], v[120:123], v[196:199], v[40:43]
	v_mfma_f32_16x16x32_bf16 v[28:31], v[104:107], v[204:207], v[28:31]
	v_mfma_f32_16x16x32_bf16 v[24:27], v[120:123], v[204:207], v[24:27]
	v_mfma_f32_16x16x32_bf16 v[12:15], v[104:107], v[216:219], v[12:15]
	v_mfma_f32_16x16x32_bf16 v[8:11], v[120:123], v[216:219], v[8:11]
	v_mfma_f32_16x16x32_bf16 v[60:63], v[108:111], v[192:195], v[60:63]
	v_mfma_f32_16x16x32_bf16 v[56:59], v[124:127], v[192:195], v[56:59]
	v_mfma_f32_16x16x32_bf16 v[44:47], v[108:111], v[200:203], v[44:47]
	v_mfma_f32_16x16x32_bf16 v[40:43], v[124:127], v[200:203], v[40:43]
	v_mfma_f32_16x16x32_bf16 v[28:31], v[108:111], v[212:215], v[28:31]
	v_mfma_f32_16x16x32_bf16 v[24:27], v[124:127], v[212:215], v[24:27]
	v_mfma_f32_16x16x32_bf16 v[12:15], v[108:111], v[220:223], v[12:15]
	v_mfma_f32_16x16x32_bf16 v[8:11], v[124:127], v[220:223], v[8:11]
	s_setprio 0
	s_setprio 1
	v_mfma_f32_16x16x32_bf16 v[52:55], v[160:163], v[188:191], v[52:55]
	v_mfma_f32_16x16x32_bf16 v[48:51], v[180:183], v[188:191], v[48:51]
	v_mfma_f32_16x16x32_bf16 v[36:39], v[160:163], v[196:199], v[36:39]
	v_mfma_f32_16x16x32_bf16 v[32:35], v[180:183], v[196:199], v[32:35]
	v_mfma_f32_16x16x32_bf16 v[20:23], v[160:163], v[204:207], v[20:23]
	v_mfma_f32_16x16x32_bf16 v[16:19], v[180:183], v[204:207], v[16:19]
	v_mfma_f32_16x16x32_bf16 v[4:7], v[160:163], v[216:219], v[4:7]
	v_mfma_f32_16x16x32_bf16 v[0:3], v[180:183], v[216:219], v[0:3]
	v_mfma_f32_16x16x32_bf16 v[52:55], v[176:179], v[192:195], v[52:55]
	v_mfma_f32_16x16x32_bf16 v[48:51], v[184:187], v[192:195], v[48:51]
	v_mfma_f32_16x16x32_bf16 v[36:39], v[176:179], v[200:203], v[36:39]
	v_mfma_f32_16x16x32_bf16 v[32:35], v[184:187], v[200:203], v[32:35]
	v_mfma_f32_16x16x32_bf16 v[20:23], v[176:179], v[212:215], v[20:23]
	v_mfma_f32_16x16x32_bf16 v[16:19], v[184:187], v[212:215], v[16:19]
	v_mfma_f32_16x16x32_bf16 v[4:7], v[176:179], v[220:223], v[4:7]
	v_mfma_f32_16x16x32_bf16 v[0:3], v[184:187], v[220:223], v[0:3]
	s_setprio 0
	s_barrier
	s_add_i32 s91, 0, 0x18000
	s_add_i32 s92, 0, 0x1c000
	v_add_u32_e32 v124, s91, v168
	v_add_u32_e32 v166, s92, v168
	ds_read_b128 v[104:107], v124
	ds_read_b128 v[108:111], v124 offset:1024
	ds_read_b128 v[120:123], v124 offset:2048
	ds_read_b128 v[124:127], v124 offset:3072
	ds_read_b128 v[160:163], v166
	ds_read_b128 v[176:179], v166 offset:1024
	ds_read_b128 v[180:183], v166 offset:2048
	ds_read_b128 v[184:187], v166 offset:3072
	s_add_u32 s56, s56, 0x40000
	s_addc_u32 s57, s57, 0
	s_mov_b32 m0, s66
	v_lshl_add_u64 v[230:231], s[56:57], 0, v[144:145]
	ds_read_b128 v[188:191], v173 offset:32768
	ds_read_b128 v[192:195], v173 offset:33792
	ds_read_b128 v[196:199], v173 offset:34816
	ds_read_b128 v[200:203], v173 offset:35840
	ds_read_b128 v[204:207], v173 offset:36864
	ds_read_b128 v[212:215], v173 offset:37888
	ds_read_b128 v[216:219], v173 offset:38912
	ds_read_b128 v[220:223], v173 offset:39936
	global_load_lds_dwordx4 v[230:231], off
	v_lshl_add_u64 v[230:231], s[56:57], 0, v[148:149]
	s_mov_b32 m0, s67
	s_nop 0
	global_load_lds_dwordx4 v[230:231], off
	s_waitcnt vmcnt(8)
	s_waitcnt lgkmcnt(0)
	s_setprio 1
	s_barrier
	v_mfma_f32_16x16x32_bf16 v[140:143], v[104:107], v[188:191], v[140:143]
	v_mfma_f32_16x16x32_bf16 v[136:139], v[120:123], v[188:191], v[136:139]
	v_mfma_f32_16x16x32_bf16 v[116:119], v[104:107], v[196:199], v[116:119]
	v_mfma_f32_16x16x32_bf16 v[112:115], v[120:123], v[196:199], v[112:115]
	v_mfma_f32_16x16x32_bf16 v[92:95], v[104:107], v[204:207], v[92:95]
	v_mfma_f32_16x16x32_bf16 v[88:91], v[120:123], v[204:207], v[88:91]
	v_mfma_f32_16x16x32_bf16 v[76:79], v[104:107], v[216:219], v[76:79]
	v_mfma_f32_16x16x32_bf16 v[72:75], v[120:123], v[216:219], v[72:75]
	v_mfma_f32_16x16x32_bf16 v[140:143], v[108:111], v[192:195], v[140:143]
	v_mfma_f32_16x16x32_bf16 v[136:139], v[124:127], v[192:195], v[136:139]
	v_mfma_f32_16x16x32_bf16 v[116:119], v[108:111], v[200:203], v[116:119]
	v_mfma_f32_16x16x32_bf16 v[112:115], v[124:127], v[200:203], v[112:115]
	v_mfma_f32_16x16x32_bf16 v[92:95], v[108:111], v[212:215], v[92:95]
	v_mfma_f32_16x16x32_bf16 v[88:91], v[124:127], v[212:215], v[88:91]
	v_mfma_f32_16x16x32_bf16 v[76:79], v[108:111], v[220:223], v[76:79]
	v_mfma_f32_16x16x32_bf16 v[72:75], v[124:127], v[220:223], v[72:75]
	s_setprio 0
	s_setprio 1
	v_mfma_f32_16x16x32_bf16 v[132:135], v[160:163], v[188:191], v[132:135]
	v_mfma_f32_16x16x32_bf16 v[128:131], v[180:183], v[188:191], v[128:131]
	v_mfma_f32_16x16x32_bf16 v[100:103], v[160:163], v[196:199], v[100:103]
	v_mfma_f32_16x16x32_bf16 v[96:99], v[180:183], v[196:199], v[96:99]
	v_mfma_f32_16x16x32_bf16 v[84:87], v[160:163], v[204:207], v[84:87]
	v_mfma_f32_16x16x32_bf16 v[80:83], v[180:183], v[204:207], v[80:83]
	v_mfma_f32_16x16x32_bf16 v[68:71], v[160:163], v[216:219], v[68:71]
	v_mfma_f32_16x16x32_bf16 v[64:67], v[180:183], v[216:219], v[64:67]
	v_mfma_f32_16x16x32_bf16 v[132:135], v[176:179], v[192:195], v[132:135]
	v_mfma_f32_16x16x32_bf16 v[128:131], v[184:187], v[192:195], v[128:131]
	v_mfma_f32_16x16x32_bf16 v[100:103], v[176:179], v[200:203], v[100:103]
	v_mfma_f32_16x16x32_bf16 v[96:99], v[184:187], v[200:203], v[96:99]
	v_mfma_f32_16x16x32_bf16 v[84:87], v[176:179], v[212:215], v[84:87]
	v_mfma_f32_16x16x32_bf16 v[80:83], v[184:187], v[212:215], v[80:83]
	v_mfma_f32_16x16x32_bf16 v[68:71], v[176:179], v[220:223], v[68:71]
	v_mfma_f32_16x16x32_bf16 v[64:67], v[184:187], v[220:223], v[64:67]
	s_setprio 0
	s_barrier
	s_add_i32 s56, s91, s58
	v_lshl_add_u64 v[164:165], v[164:165], 0, s[14:15]
	s_mov_b32 m0, s56
	ds_read_b128 v[188:191], v173 offset:49152
	ds_read_b128 v[192:195], v173 offset:50176
	ds_read_b128 v[196:199], v173 offset:51200
	ds_read_b128 v[200:203], v173 offset:52224
	ds_read_b128 v[204:207], v173 offset:53248
	ds_read_b128 v[212:215], v173 offset:54272
	ds_read_b128 v[216:219], v173 offset:55296
	ds_read_b128 v[220:223], v173 offset:56320
	global_load_lds_dwordx4 v[164:165], off
	s_add_i32 m0, s56, 0x2000
	s_add_u32 s54, s54, 0x40080
	v_lshl_add_u64 v[164:165], v[224:225], 0, s[14:15]
	s_addc_u32 s55, s55, 0
	s_add_i32 s56, s92, s58
	global_load_lds_dwordx4 v[164:165], off
	v_lshl_add_u64 v[164:165], s[54:55], 0, v[146:147]
	s_mov_b32 m0, s56
	s_nop 0
	global_load_lds_dwordx4 v[164:165], off
	v_lshl_add_u64 v[164:165], s[54:55], 0, v[150:151]
	s_add_i32 m0, s56, 0x2000
	s_nop 0
	global_load_lds_dwordx4 v[164:165], off
	v_lshl_add_u64 v[164:165], v[226:227], 0, s[14:15]
	s_mov_b32 m0, s72
	s_nop 0
	global_load_lds_dwordx4 v[164:165], off
	v_lshl_add_u64 v[164:165], v[228:229], 0, s[14:15]
	s_mov_b32 m0, s73
	s_nop 0
	global_load_lds_dwordx4 v[164:165], off
	s_waitcnt vmcnt(8)
	s_waitcnt lgkmcnt(0)
	s_setprio 1
	s_barrier
	v_mfma_f32_16x16x32_bf16 v[60:63], v[104:107], v[188:191], v[60:63]
	v_mfma_f32_16x16x32_bf16 v[56:59], v[120:123], v[188:191], v[56:59]
	v_mfma_f32_16x16x32_bf16 v[44:47], v[104:107], v[196:199], v[44:47]
	v_mfma_f32_16x16x32_bf16 v[40:43], v[120:123], v[196:199], v[40:43]
	v_mfma_f32_16x16x32_bf16 v[28:31], v[104:107], v[204:207], v[28:31]
	v_mfma_f32_16x16x32_bf16 v[24:27], v[120:123], v[204:207], v[24:27]
	v_mfma_f32_16x16x32_bf16 v[12:15], v[104:107], v[216:219], v[12:15]
	v_mfma_f32_16x16x32_bf16 v[8:11], v[120:123], v[216:219], v[8:11]
	v_mfma_f32_16x16x32_bf16 v[60:63], v[108:111], v[192:195], v[60:63]
	v_mfma_f32_16x16x32_bf16 v[56:59], v[124:127], v[192:195], v[56:59]
	v_mfma_f32_16x16x32_bf16 v[44:47], v[108:111], v[200:203], v[44:47]
	v_mfma_f32_16x16x32_bf16 v[40:43], v[124:127], v[200:203], v[40:43]
	v_mfma_f32_16x16x32_bf16 v[28:31], v[108:111], v[212:215], v[28:31]
	v_mfma_f32_16x16x32_bf16 v[24:27], v[124:127], v[212:215], v[24:27]
	v_mfma_f32_16x16x32_bf16 v[12:15], v[108:111], v[220:223], v[12:15]
	v_mfma_f32_16x16x32_bf16 v[8:11], v[124:127], v[220:223], v[8:11]
	s_setprio 0
	s_setprio 1
	v_mfma_f32_16x16x32_bf16 v[52:55], v[160:163], v[188:191], v[52:55]
	v_mfma_f32_16x16x32_bf16 v[48:51], v[180:183], v[188:191], v[48:51]
	v_mfma_f32_16x16x32_bf16 v[36:39], v[160:163], v[196:199], v[36:39]
	v_mfma_f32_16x16x32_bf16 v[32:35], v[180:183], v[196:199], v[32:35]
	v_mfma_f32_16x16x32_bf16 v[20:23], v[160:163], v[204:207], v[20:23]
	v_mfma_f32_16x16x32_bf16 v[16:19], v[180:183], v[204:207], v[16:19]
	v_mfma_f32_16x16x32_bf16 v[4:7], v[160:163], v[216:219], v[4:7]
	v_mfma_f32_16x16x32_bf16 v[0:3], v[180:183], v[216:219], v[0:3]
	s_add_i32 s88, s88, 2
	s_add_u32 s52, s52, 0x100
	s_addc_u32 s53, s53, 0
	s_add_u32 s86, s86, 0x100
	s_addc_u32 s87, s87, 0
	s_cmp_gt_u32 s88, 13
	v_mfma_f32_16x16x32_bf16 v[52:55], v[176:179], v[192:195], v[52:55]
	v_mfma_f32_16x16x32_bf16 v[48:51], v[184:187], v[192:195], v[48:51]
	v_mfma_f32_16x16x32_bf16 v[36:39], v[176:179], v[200:203], v[36:39]
	v_mfma_f32_16x16x32_bf16 v[32:35], v[184:187], v[200:203], v[32:35]
	v_mfma_f32_16x16x32_bf16 v[20:23], v[176:179], v[212:215], v[20:23]
	v_mfma_f32_16x16x32_bf16 v[16:19], v[184:187], v[212:215], v[16:19]
	v_mfma_f32_16x16x32_bf16 v[4:7], v[176:179], v[220:223], v[4:7]
	v_mfma_f32_16x16x32_bf16 v[0:3], v[184:187], v[220:223], v[0:3]
	s_setprio 0
	s_barrier
	s_cbranch_scc0 .LBB0_197
	s_and_b64 vcc, exec, s[16:17]
	s_cbranch_vccz .LBB0_200
	s_barrier

.LBB0_591:
	ds_read_b128 v[152:155], v179
	ds_read_b128 v[156:159], v179 offset:1024
	ds_read_b128 v[160:163], v179 offset:2048
	ds_read_b128 v[164:167], v179 offset:3072
	ds_read_b128 v[168:171], v180
	ds_read_b128 v[172:175], v180 offset:1024
	ds_read_b128 v[184:187], v180 offset:2048
	ds_read_b128 v[188:191], v180 offset:3072
	s_add_u32 s52, s50, 0xfffc0080
	s_addc_u32 s53, s51, -1
	s_cmp_eq_u32 s75, 12
	s_cselect_b32 s55, s9, s53
	s_cselect_b32 s54, s43, s52
	s_cselect_b32 s53, s41, s74
	s_cselect_b32 s52, s49, s73
	v_lshl_add_u64 v[228:229], s[50:51], 0, v[136:137]
	s_add_i32 m0, s61, 0xc000
	ds_read_b128 v[192:195], v181
	ds_read_b128 v[196:199], v181 offset:1024
	ds_read_b128 v[200:203], v181 offset:2048
	ds_read_b128 v[204:207], v181 offset:3072
	ds_read_b128 v[212:215], v181 offset:4096
	ds_read_b128 v[216:219], v181 offset:5120
	ds_read_b128 v[220:223], v181 offset:6144
	ds_read_b128 v[224:227], v181 offset:7168
	global_load_lds_dwordx4 v[228:229], off
	v_lshl_add_u64 v[228:229], s[50:51], 0, v[138:139]
	s_add_i32 m0, s61, 0xe000
	s_nop 0
	global_load_lds_dwordx4 v[228:229], off
	s_waitcnt vmcnt(8)
	s_waitcnt lgkmcnt(0)
	s_setprio 1
	s_barrier
	v_mfma_f32_16x16x32_bf16 v[124:127], v[152:155], v[192:195], v[124:127]
	v_mfma_f32_16x16x32_bf16 v[120:123], v[160:163], v[192:195], v[120:123]
	v_mfma_f32_16x16x32_bf16 v[108:111], v[152:155], v[200:203], v[108:111]
	v_mfma_f32_16x16x32_bf16 v[104:107], v[160:163], v[200:203], v[104:107]
	v_mfma_f32_16x16x32_bf16 v[92:95], v[152:155], v[212:215], v[92:95]
	v_mfma_f32_16x16x32_bf16 v[88:91], v[160:163], v[212:215], v[88:91]
	v_mfma_f32_16x16x32_bf16 v[76:79], v[152:155], v[220:223], v[76:79]
	v_mfma_f32_16x16x32_bf16 v[72:75], v[160:163], v[220:223], v[72:75]
	v_mfma_f32_16x16x32_bf16 v[124:127], v[156:159], v[196:199], v[124:127]
	v_mfma_f32_16x16x32_bf16 v[120:123], v[164:167], v[196:199], v[120:123]
	v_mfma_f32_16x16x32_bf16 v[108:111], v[156:159], v[204:207], v[108:111]
	v_mfma_f32_16x16x32_bf16 v[104:107], v[164:167], v[204:207], v[104:107]
	v_mfma_f32_16x16x32_bf16 v[92:95], v[156:159], v[216:219], v[92:95]
	v_mfma_f32_16x16x32_bf16 v[88:91], v[164:167], v[216:219], v[88:91]
	v_mfma_f32_16x16x32_bf16 v[76:79], v[156:159], v[224:227], v[76:79]
	v_mfma_f32_16x16x32_bf16 v[72:75], v[164:167], v[224:227], v[72:75]
	s_setprio 0
	s_setprio 1
	v_mfma_f32_16x16x32_bf16 v[116:119], v[168:171], v[192:195], v[116:119]
	v_mfma_f32_16x16x32_bf16 v[112:115], v[184:187], v[192:195], v[112:115]
	v_mfma_f32_16x16x32_bf16 v[100:103], v[168:171], v[200:203], v[100:103]
	v_mfma_f32_16x16x32_bf16 v[96:99], v[184:187], v[200:203], v[96:99]
	v_mfma_f32_16x16x32_bf16 v[84:87], v[168:171], v[212:215], v[84:87]
	v_mfma_f32_16x16x32_bf16 v[80:83], v[184:187], v[212:215], v[80:83]
	v_mfma_f32_16x16x32_bf16 v[68:71], v[168:171], v[220:223], v[68:71]
	v_mfma_f32_16x16x32_bf16 v[64:67], v[184:187], v[220:223], v[64:67]
	v_mfma_f32_16x16x32_bf16 v[116:119], v[172:175], v[196:199], v[116:119]
	v_mfma_f32_16x16x32_bf16 v[112:115], v[188:191], v[196:199], v[112:115]
	v_mfma_f32_16x16x32_bf16 v[100:103], v[172:175], v[204:207], v[100:103]
	v_mfma_f32_16x16x32_bf16 v[96:99], v[188:191], v[204:207], v[96:99]
	v_mfma_f32_16x16x32_bf16 v[84:87], v[172:175], v[216:219], v[84:87]
	v_mfma_f32_16x16x32_bf16 v[80:83], v[188:191], v[216:219], v[80:83]
	v_mfma_f32_16x16x32_bf16 v[68:71], v[172:175], v[224:227], v[68:71]
	v_mfma_f32_16x16x32_bf16 v[64:67], v[188:191], v[224:227], v[64:67]
	s_setprio 0
	s_barrier
	s_add_i32 s76, s71, s60
	v_lshl_add_u64 v[228:229], s[52:53], 0, v[130:131]
	s_mov_b32 m0, s76
	ds_read_b128 v[192:195], v181 offset:16384
	ds_read_b128 v[196:199], v181 offset:17408
	ds_read_b128 v[200:203], v181 offset:18432
	ds_read_b128 v[204:207], v181 offset:19456
	ds_read_b128 v[212:215], v181 offset:20480
	ds_read_b128 v[216:219], v181 offset:21504
	ds_read_b128 v[220:223], v181 offset:22528
	ds_read_b128 v[224:227], v181 offset:23552
	global_load_lds_dwordx4 v[228:229], off
	s_add_i32 m0, s76, 0x2000
	s_add_u32 s76, s52, 0x40000
	v_lshl_add_u64 v[230:231], s[52:53], 0, v[134:135]
	s_addc_u32 s77, s53, 0
	s_add_i32 s78, s72, s60
	global_load_lds_dwordx4 v[230:231], off
	v_lshl_add_u64 v[232:233], s[76:77], 0, v[130:131]
	s_mov_b32 m0, s78
	v_lshl_add_u64 v[234:235], s[54:55], 0, v[132:133]
	global_load_lds_dwordx4 v[232:233], off
	v_lshl_add_u64 v[232:233], s[76:77], 0, v[134:135]
	s_add_i32 m0, s78, 0x2000
	s_nop 0
	global_load_lds_dwordx4 v[232:233], off
	v_lshl_add_u64 v[232:233], s[54:55], 0, v[128:129]
	s_mov_b32 m0, s61
	s_nop 0
	global_load_lds_dwordx4 v[232:233], off
	s_mov_b32 m0, s62
	s_nop 0
	global_load_lds_dwordx4 v[234:235], off
	s_waitcnt vmcnt(8)
	s_waitcnt lgkmcnt(0)
	s_setprio 1
	s_barrier
	v_mfma_f32_16x16x32_bf16 v[60:63], v[152:155], v[192:195], v[60:63]
	v_mfma_f32_16x16x32_bf16 v[56:59], v[160:163], v[192:195], v[56:59]
	v_mfma_f32_16x16x32_bf16 v[44:47], v[152:155], v[200:203], v[44:47]
	v_mfma_f32_16x16x32_bf16 v[40:43], v[160:163], v[200:203], v[40:43]
	v_mfma_f32_16x16x32_bf16 v[28:31], v[152:155], v[212:215], v[28:31]
	v_mfma_f32_16x16x32_bf16 v[24:27], v[160:163], v[212:215], v[24:27]
	v_mfma_f32_16x16x32_bf16 v[12:15], v[152:155], v[220:223], v[12:15]
	v_mfma_f32_16x16x32_bf16 v[8:11], v[160:163], v[220:223], v[8:11]
	v_mfma_f32_16x16x32_bf16 v[60:63], v[156:159], v[196:199], v[60:63]
	v_mfma_f32_16x16x32_bf16 v[56:59], v[164:167], v[196:199], v[56:59]
	v_mfma_f32_16x16x32_bf16 v[44:47], v[156:159], v[204:207], v[44:47]
	v_mfma_f32_16x16x32_bf16 v[40:43], v[164:167], v[204:207], v[40:43]
	v_mfma_f32_16x16x32_bf16 v[28:31], v[156:159], v[216:219], v[28:31]
	v_mfma_f32_16x16x32_bf16 v[24:27], v[164:167], v[216:219], v[24:27]
	v_mfma_f32_16x16x32_bf16 v[12:15], v[156:159], v[224:227], v[12:15]
	v_mfma_f32_16x16x32_bf16 v[8:11], v[164:167], v[224:227], v[8:11]
	s_setprio 0
	s_setprio 1
	v_mfma_f32_16x16x32_bf16 v[52:55], v[168:171], v[192:195], v[52:55]
	v_mfma_f32_16x16x32_bf16 v[48:51], v[184:187], v[192:195], v[48:51]
	v_mfma_f32_16x16x32_bf16 v[36:39], v[168:171], v[200:203], v[36:39]
	v_mfma_f32_16x16x32_bf16 v[32:35], v[184:187], v[200:203], v[32:35]
	v_mfma_f32_16x16x32_bf16 v[20:23], v[168:171], v[212:215], v[20:23]
	v_mfma_f32_16x16x32_bf16 v[16:19], v[184:187], v[212:215], v[16:19]
	v_mfma_f32_16x16x32_bf16 v[4:7], v[168:171], v[220:223], v[4:7]
	v_mfma_f32_16x16x32_bf16 v[0:3], v[184:187], v[220:223], v[0:3]
	v_mfma_f32_16x16x32_bf16 v[52:55], v[172:175], v[196:199], v[52:55]
	v_mfma_f32_16x16x32_bf16 v[48:51], v[188:191], v[196:199], v[48:51]
	v_mfma_f32_16x16x32_bf16 v[36:39], v[172:175], v[204:207], v[36:39]
	v_mfma_f32_16x16x32_bf16 v[32:35], v[188:191], v[204:207], v[32:35]
	v_mfma_f32_16x16x32_bf16 v[20:23], v[172:175], v[216:219], v[20:23]
	v_mfma_f32_16x16x32_bf16 v[16:19], v[188:191], v[216:219], v[16:19]
	v_mfma_f32_16x16x32_bf16 v[4:7], v[172:175], v[224:227], v[4:7]
	v_mfma_f32_16x16x32_bf16 v[0:3], v[188:191], v[224:227], v[0:3]
	s_setprio 0
	s_barrier
	s_add_i32 s76, 0, 0x18000
	s_add_i32 s77, 0, 0x1c000
	v_add_u32_e32 v164, s76, v177
	v_add_u32_e32 v183, s77, v177
	ds_read_b128 v[152:155], v164
	ds_read_b128 v[156:159], v164 offset:1024
	ds_read_b128 v[160:163], v164 offset:2048
	ds_read_b128 v[164:167], v164 offset:3072
	ds_read_b128 v[168:171], v183
	ds_read_b128 v[172:175], v183 offset:1024
	ds_read_b128 v[184:187], v183 offset:2048
	ds_read_b128 v[188:191], v183 offset:3072
	s_add_u32 s54, s54, 0x40000
	s_addc_u32 s55, s55, 0
	s_mov_b32 m0, s63
	v_lshl_add_u64 v[236:237], s[54:55], 0, v[128:129]
	ds_read_b128 v[192:195], v181 offset:32768
	ds_read_b128 v[196:199], v181 offset:33792
	ds_read_b128 v[200:203], v181 offset:34816
	ds_read_b128 v[204:207], v181 offset:35840
	ds_read_b128 v[212:215], v181 offset:36864
	ds_read_b128 v[216:219], v181 offset:37888
	ds_read_b128 v[220:223], v181 offset:38912
	ds_read_b128 v[224:227], v181 offset:39936
	global_load_lds_dwordx4 v[236:237], off
	v_lshl_add_u64 v[236:237], s[54:55], 0, v[132:133]
	s_mov_b32 m0, s64
	s_nop 0
	global_load_lds_dwordx4 v[236:237], off
	s_waitcnt vmcnt(8)
	s_waitcnt lgkmcnt(0)
	s_setprio 1
	s_barrier
	v_mfma_f32_16x16x32_bf16 v[124:127], v[152:155], v[192:195], v[124:127]
	v_mfma_f32_16x16x32_bf16 v[120:123], v[160:163], v[192:195], v[120:123]
	v_mfma_f32_16x16x32_bf16 v[108:111], v[152:155], v[200:203], v[108:111]
	v_mfma_f32_16x16x32_bf16 v[104:107], v[160:163], v[200:203], v[104:107]
	v_mfma_f32_16x16x32_bf16 v[92:95], v[152:155], v[212:215], v[92:95]
	v_mfma_f32_16x16x32_bf16 v[88:91], v[160:163], v[212:215], v[88:91]
	v_mfma_f32_16x16x32_bf16 v[76:79], v[152:155], v[220:223], v[76:79]
	v_mfma_f32_16x16x32_bf16 v[72:75], v[160:163], v[220:223], v[72:75]
	v_mfma_f32_16x16x32_bf16 v[124:127], v[156:159], v[196:199], v[124:127]
	v_mfma_f32_16x16x32_bf16 v[120:123], v[164:167], v[196:199], v[120:123]
	v_mfma_f32_16x16x32_bf16 v[108:111], v[156:159], v[204:207], v[108:111]
	v_mfma_f32_16x16x32_bf16 v[104:107], v[164:167], v[204:207], v[104:107]
	v_mfma_f32_16x16x32_bf16 v[92:95], v[156:159], v[216:219], v[92:95]
	v_mfma_f32_16x16x32_bf16 v[88:91], v[164:167], v[216:219], v[88:91]
	v_mfma_f32_16x16x32_bf16 v[76:79], v[156:159], v[224:227], v[76:79]
	v_mfma_f32_16x16x32_bf16 v[72:75], v[164:167], v[224:227], v[72:75]
	s_setprio 0
	s_setprio 1
	v_mfma_f32_16x16x32_bf16 v[116:119], v[168:171], v[192:195], v[116:119]
	v_mfma_f32_16x16x32_bf16 v[112:115], v[184:187], v[192:195], v[112:115]
	v_mfma_f32_16x16x32_bf16 v[100:103], v[168:171], v[200:203], v[100:103]
	v_mfma_f32_16x16x32_bf16 v[96:99], v[184:187], v[200:203], v[96:99]
	v_mfma_f32_16x16x32_bf16 v[84:87], v[168:171], v[212:215], v[84:87]
	v_mfma_f32_16x16x32_bf16 v[80:83], v[184:187], v[212:215], v[80:83]
	v_mfma_f32_16x16x32_bf16 v[68:71], v[168:171], v[220:223], v[68:71]
	v_mfma_f32_16x16x32_bf16 v[64:67], v[184:187], v[220:223], v[64:67]
	v_mfma_f32_16x16x32_bf16 v[116:119], v[172:175], v[196:199], v[116:119]
	v_mfma_f32_16x16x32_bf16 v[112:115], v[188:191], v[196:199], v[112:115]
	v_mfma_f32_16x16x32_bf16 v[100:103], v[172:175], v[204:207], v[100:103]
	v_mfma_f32_16x16x32_bf16 v[96:99], v[188:191], v[204:207], v[96:99]
	v_mfma_f32_16x16x32_bf16 v[84:87], v[172:175], v[216:219], v[84:87]
	v_mfma_f32_16x16x32_bf16 v[80:83], v[188:191], v[216:219], v[80:83]
	v_mfma_f32_16x16x32_bf16 v[68:71], v[172:175], v[224:227], v[68:71]
	v_mfma_f32_16x16x32_bf16 v[64:67], v[188:191], v[224:227], v[64:67]
	s_setprio 0
	s_barrier
	s_add_i32 s54, s76, s60
	v_lshl_add_u64 v[228:229], v[228:229], 0, s[24:25]
	s_mov_b32 m0, s54
	ds_read_b128 v[192:195], v181 offset:49152
	ds_read_b128 v[196:199], v181 offset:50176
	ds_read_b128 v[200:203], v181 offset:51200
	ds_read_b128 v[204:207], v181 offset:52224
	ds_read_b128 v[212:215], v181 offset:53248
	ds_read_b128 v[216:219], v181 offset:54272
	ds_read_b128 v[220:223], v181 offset:55296
	ds_read_b128 v[224:227], v181 offset:56320
	global_load_lds_dwordx4 v[228:229], off
	s_add_i32 m0, s54, 0x2000
	s_add_u32 s52, s52, 0x40080
	v_lshl_add_u64 v[228:229], v[230:231], 0, s[24:25]
	s_addc_u32 s53, s53, 0
	s_add_i32 s54, s77, s60
	global_load_lds_dwordx4 v[228:229], off
	v_lshl_add_u64 v[228:229], s[52:53], 0, v[130:131]
	s_mov_b32 m0, s54
	s_nop 0
	global_load_lds_dwordx4 v[228:229], off
	v_lshl_add_u64 v[228:229], s[52:53], 0, v[134:135]
	s_add_i32 m0, s54, 0x2000
	s_nop 0
	global_load_lds_dwordx4 v[228:229], off
	v_lshl_add_u64 v[228:229], v[232:233], 0, s[24:25]
	s_mov_b32 m0, s66
	s_nop 0
	global_load_lds_dwordx4 v[228:229], off
	v_lshl_add_u64 v[228:229], v[234:235], 0, s[24:25]
	s_mov_b32 m0, s67
	s_nop 0
	global_load_lds_dwordx4 v[228:229], off
	s_waitcnt vmcnt(8)
	s_waitcnt lgkmcnt(0)
	s_setprio 1
	s_barrier
	v_mfma_f32_16x16x32_bf16 v[60:63], v[152:155], v[192:195], v[60:63]
	v_mfma_f32_16x16x32_bf16 v[56:59], v[160:163], v[192:195], v[56:59]
	v_mfma_f32_16x16x32_bf16 v[44:47], v[152:155], v[200:203], v[44:47]
	v_mfma_f32_16x16x32_bf16 v[40:43], v[160:163], v[200:203], v[40:43]
	v_mfma_f32_16x16x32_bf16 v[28:31], v[152:155], v[212:215], v[28:31]
	v_mfma_f32_16x16x32_bf16 v[24:27], v[160:163], v[212:215], v[24:27]
	v_mfma_f32_16x16x32_bf16 v[12:15], v[152:155], v[220:223], v[12:15]
	v_mfma_f32_16x16x32_bf16 v[8:11], v[160:163], v[220:223], v[8:11]
	v_mfma_f32_16x16x32_bf16 v[60:63], v[156:159], v[196:199], v[60:63]
	v_mfma_f32_16x16x32_bf16 v[56:59], v[164:167], v[196:199], v[56:59]
	v_mfma_f32_16x16x32_bf16 v[44:47], v[156:159], v[204:207], v[44:47]
	v_mfma_f32_16x16x32_bf16 v[40:43], v[164:167], v[204:207], v[40:43]
	v_mfma_f32_16x16x32_bf16 v[28:31], v[156:159], v[216:219], v[28:31]
	v_mfma_f32_16x16x32_bf16 v[24:27], v[164:167], v[216:219], v[24:27]
	v_mfma_f32_16x16x32_bf16 v[12:15], v[156:159], v[224:227], v[12:15]
	v_mfma_f32_16x16x32_bf16 v[8:11], v[164:167], v[224:227], v[8:11]
	s_setprio 0
	s_setprio 1
	v_mfma_f32_16x16x32_bf16 v[52:55], v[168:171], v[192:195], v[52:55]
	v_mfma_f32_16x16x32_bf16 v[48:51], v[184:187], v[192:195], v[48:51]
	v_mfma_f32_16x16x32_bf16 v[36:39], v[168:171], v[200:203], v[36:39]
	v_mfma_f32_16x16x32_bf16 v[32:35], v[184:187], v[200:203], v[32:35]
	v_mfma_f32_16x16x32_bf16 v[20:23], v[168:171], v[212:215], v[20:23]
	v_mfma_f32_16x16x32_bf16 v[16:19], v[184:187], v[212:215], v[16:19]
	v_mfma_f32_16x16x32_bf16 v[4:7], v[168:171], v[220:223], v[4:7]
	v_mfma_f32_16x16x32_bf16 v[0:3], v[184:187], v[220:223], v[0:3]
	s_add_i32 s75, s75, 2
	s_add_u32 s50, s50, 0x100
	s_addc_u32 s51, s51, 0
	s_add_u32 s73, s73, 0x100
	s_addc_u32 s74, s74, 0
	s_cmp_gt_u32 s75, 13
	v_mfma_f32_16x16x32_bf16 v[52:55], v[172:175], v[196:199], v[52:55]
	v_mfma_f32_16x16x32_bf16 v[48:51], v[188:191], v[196:199], v[48:51]
	v_mfma_f32_16x16x32_bf16 v[36:39], v[172:175], v[204:207], v[36:39]
	v_mfma_f32_16x16x32_bf16 v[32:35], v[188:191], v[204:207], v[32:35]
	v_mfma_f32_16x16x32_bf16 v[20:23], v[172:175], v[216:219], v[20:23]
	v_mfma_f32_16x16x32_bf16 v[16:19], v[188:191], v[216:219], v[16:19]
	v_mfma_f32_16x16x32_bf16 v[4:7], v[172:175], v[224:227], v[4:7]
	v_mfma_f32_16x16x32_bf16 v[0:3], v[188:191], v[224:227], v[0:3]
	s_setprio 0
	s_barrier
	s_cbranch_scc0 .LBB0_591
	s_and_b64 vcc, exec, s[36:37]
	s_cbranch_vccz .LBB0_594
	s_barrier

.LBB0_702:
	ds_read_b128 v[152:155], v149
	ds_read_b128 v[156:159], v149 offset:1024
	ds_read_b128 v[160:163], v149 offset:2048
	ds_read_b128 v[164:167], v149 offset:3072
	ds_read_b128 v[168:171], v150
	ds_read_b128 v[172:175], v150 offset:1024
	ds_read_b128 v[176:179], v150 offset:2048
	ds_read_b128 v[180:183], v150 offset:3072
	s_add_u32 s46, s44, 0xfffc0080
	s_addc_u32 s47, s45, -1
	s_cmp_eq_u32 s75, 12
	s_cselect_b32 s49, s37, s47
	s_cselect_b32 s48, s71, s46
	s_cselect_b32 s47, s25, s74
	s_cselect_b32 s46, s72, s73
	v_lshl_add_u64 v[144:145], s[44:45], 0, v[136:137]
	s_add_i32 m0, s43, 0xc000
	ds_read_b128 v[184:187], v151
	ds_read_b128 v[188:191], v151 offset:1024
	ds_read_b128 v[192:195], v151 offset:2048
	ds_read_b128 v[196:199], v151 offset:3072
	ds_read_b128 v[200:203], v151 offset:4096
	ds_read_b128 v[204:207], v151 offset:5120
	ds_read_b128 v[212:215], v151 offset:6144
	ds_read_b128 v[216:219], v151 offset:7168
	global_load_lds_dwordx4 v[144:145], off
	v_lshl_add_u64 v[144:145], s[44:45], 0, v[138:139]
	s_add_i32 m0, s43, 0xe000
	s_nop 0
	global_load_lds_dwordx4 v[144:145], off
	s_waitcnt vmcnt(8)
	s_waitcnt lgkmcnt(0)
	s_setprio 1
	s_barrier
	v_mfma_f32_16x16x32_bf16 v[124:127], v[152:155], v[184:187], v[124:127]
	v_mfma_f32_16x16x32_bf16 v[120:123], v[160:163], v[184:187], v[120:123]
	v_mfma_f32_16x16x32_bf16 v[108:111], v[152:155], v[192:195], v[108:111]
	v_mfma_f32_16x16x32_bf16 v[104:107], v[160:163], v[192:195], v[104:107]
	v_mfma_f32_16x16x32_bf16 v[92:95], v[152:155], v[200:203], v[92:95]
	v_mfma_f32_16x16x32_bf16 v[88:91], v[160:163], v[200:203], v[88:91]
	v_mfma_f32_16x16x32_bf16 v[76:79], v[152:155], v[212:215], v[76:79]
	v_mfma_f32_16x16x32_bf16 v[72:75], v[160:163], v[212:215], v[72:75]
	v_mfma_f32_16x16x32_bf16 v[124:127], v[156:159], v[188:191], v[124:127]
	v_mfma_f32_16x16x32_bf16 v[120:123], v[164:167], v[188:191], v[120:123]
	v_mfma_f32_16x16x32_bf16 v[108:111], v[156:159], v[196:199], v[108:111]
	v_mfma_f32_16x16x32_bf16 v[104:107], v[164:167], v[196:199], v[104:107]
	v_mfma_f32_16x16x32_bf16 v[92:95], v[156:159], v[204:207], v[92:95]
	v_mfma_f32_16x16x32_bf16 v[88:91], v[164:167], v[204:207], v[88:91]
	v_mfma_f32_16x16x32_bf16 v[76:79], v[156:159], v[216:219], v[76:79]
	v_mfma_f32_16x16x32_bf16 v[72:75], v[164:167], v[216:219], v[72:75]
	s_setprio 0
	s_setprio 1
	v_mfma_f32_16x16x32_bf16 v[116:119], v[168:171], v[184:187], v[116:119]
	v_mfma_f32_16x16x32_bf16 v[112:115], v[176:179], v[184:187], v[112:115]
	v_mfma_f32_16x16x32_bf16 v[100:103], v[168:171], v[192:195], v[100:103]
	v_mfma_f32_16x16x32_bf16 v[96:99], v[176:179], v[192:195], v[96:99]
	v_mfma_f32_16x16x32_bf16 v[84:87], v[168:171], v[200:203], v[84:87]
	v_mfma_f32_16x16x32_bf16 v[80:83], v[176:179], v[200:203], v[80:83]
	v_mfma_f32_16x16x32_bf16 v[68:71], v[168:171], v[212:215], v[68:71]
	v_mfma_f32_16x16x32_bf16 v[64:67], v[176:179], v[212:215], v[64:67]
	v_mfma_f32_16x16x32_bf16 v[116:119], v[172:175], v[188:191], v[116:119]
	v_mfma_f32_16x16x32_bf16 v[112:115], v[180:183], v[188:191], v[112:115]
	v_mfma_f32_16x16x32_bf16 v[100:103], v[172:175], v[196:199], v[100:103]
	v_mfma_f32_16x16x32_bf16 v[96:99], v[180:183], v[196:199], v[96:99]
	v_mfma_f32_16x16x32_bf16 v[84:87], v[172:175], v[204:207], v[84:87]
	v_mfma_f32_16x16x32_bf16 v[80:83], v[180:183], v[204:207], v[80:83]
	v_mfma_f32_16x16x32_bf16 v[68:71], v[172:175], v[216:219], v[68:71]
	v_mfma_f32_16x16x32_bf16 v[64:67], v[180:183], v[216:219], v[64:67]
	s_setprio 0
	s_barrier
	s_add_i32 s76, s64, s55
	v_lshl_add_u64 v[144:145], s[46:47], 0, v[130:131]
	s_mov_b32 m0, s76
	ds_read_b128 v[184:187], v151 offset:16384
	ds_read_b128 v[188:191], v151 offset:17408
	ds_read_b128 v[192:195], v151 offset:18432
	ds_read_b128 v[196:199], v151 offset:19456
	ds_read_b128 v[200:203], v151 offset:20480
	ds_read_b128 v[204:207], v151 offset:21504
	ds_read_b128 v[212:215], v151 offset:22528
	ds_read_b128 v[216:219], v151 offset:23552
	global_load_lds_dwordx4 v[144:145], off
	s_add_i32 m0, s76, 0x2000
	s_add_u32 s76, s46, 0x40000
	v_lshl_add_u64 v[220:221], s[46:47], 0, v[134:135]
	s_addc_u32 s77, s47, 0
	s_add_i32 s78, s65, s55
	global_load_lds_dwordx4 v[220:221], off
	v_lshl_add_u64 v[222:223], s[76:77], 0, v[130:131]
	s_mov_b32 m0, s78
	v_lshl_add_u64 v[224:225], s[48:49], 0, v[132:133]
	global_load_lds_dwordx4 v[222:223], off
	v_lshl_add_u64 v[222:223], s[76:77], 0, v[134:135]
	s_add_i32 m0, s78, 0x2000
	s_nop 0
	global_load_lds_dwordx4 v[222:223], off
	v_lshl_add_u64 v[222:223], s[48:49], 0, v[128:129]
	s_mov_b32 m0, s43
	s_nop 0
	global_load_lds_dwordx4 v[222:223], off
	s_mov_b32 m0, s56
	s_nop 0
	global_load_lds_dwordx4 v[224:225], off
	s_waitcnt vmcnt(8)
	s_waitcnt lgkmcnt(0)
	s_setprio 1
	s_barrier
	v_mfma_f32_16x16x32_bf16 v[60:63], v[152:155], v[184:187], v[60:63]
	v_mfma_f32_16x16x32_bf16 v[56:59], v[160:163], v[184:187], v[56:59]
	v_mfma_f32_16x16x32_bf16 v[44:47], v[152:155], v[192:195], v[44:47]
	v_mfma_f32_16x16x32_bf16 v[40:43], v[160:163], v[192:195], v[40:43]
	v_mfma_f32_16x16x32_bf16 v[28:31], v[152:155], v[200:203], v[28:31]
	v_mfma_f32_16x16x32_bf16 v[24:27], v[160:163], v[200:203], v[24:27]
	v_mfma_f32_16x16x32_bf16 v[12:15], v[152:155], v[212:215], v[12:15]
	v_mfma_f32_16x16x32_bf16 v[8:11], v[160:163], v[212:215], v[8:11]
	v_mfma_f32_16x16x32_bf16 v[60:63], v[156:159], v[188:191], v[60:63]
	v_mfma_f32_16x16x32_bf16 v[56:59], v[164:167], v[188:191], v[56:59]
	v_mfma_f32_16x16x32_bf16 v[44:47], v[156:159], v[196:199], v[44:47]
	v_mfma_f32_16x16x32_bf16 v[40:43], v[164:167], v[196:199], v[40:43]
	v_mfma_f32_16x16x32_bf16 v[28:31], v[156:159], v[204:207], v[28:31]
	v_mfma_f32_16x16x32_bf16 v[24:27], v[164:167], v[204:207], v[24:27]
	v_mfma_f32_16x16x32_bf16 v[12:15], v[156:159], v[216:219], v[12:15]
	v_mfma_f32_16x16x32_bf16 v[8:11], v[164:167], v[216:219], v[8:11]
	s_setprio 0
	s_setprio 1
	v_mfma_f32_16x16x32_bf16 v[52:55], v[168:171], v[184:187], v[52:55]
	v_mfma_f32_16x16x32_bf16 v[48:51], v[176:179], v[184:187], v[48:51]
	v_mfma_f32_16x16x32_bf16 v[36:39], v[168:171], v[192:195], v[36:39]
	v_mfma_f32_16x16x32_bf16 v[32:35], v[176:179], v[192:195], v[32:35]
	v_mfma_f32_16x16x32_bf16 v[20:23], v[168:171], v[200:203], v[20:23]
	v_mfma_f32_16x16x32_bf16 v[16:19], v[176:179], v[200:203], v[16:19]
	v_mfma_f32_16x16x32_bf16 v[4:7], v[168:171], v[212:215], v[4:7]
	v_mfma_f32_16x16x32_bf16 v[0:3], v[176:179], v[212:215], v[0:3]
	v_mfma_f32_16x16x32_bf16 v[52:55], v[172:175], v[188:191], v[52:55]
	v_mfma_f32_16x16x32_bf16 v[48:51], v[180:183], v[188:191], v[48:51]
	v_mfma_f32_16x16x32_bf16 v[36:39], v[172:175], v[196:199], v[36:39]
	v_mfma_f32_16x16x32_bf16 v[32:35], v[180:183], v[196:199], v[32:35]
	v_mfma_f32_16x16x32_bf16 v[20:23], v[172:175], v[204:207], v[20:23]
	v_mfma_f32_16x16x32_bf16 v[16:19], v[180:183], v[204:207], v[16:19]
	v_mfma_f32_16x16x32_bf16 v[4:7], v[172:175], v[216:219], v[4:7]
	v_mfma_f32_16x16x32_bf16 v[0:3], v[180:183], v[216:219], v[0:3]
	s_setprio 0
	s_barrier
	s_add_i32 s76, 0, 0x18000
	s_add_i32 s77, 0, 0x1c000
	v_add_u32_e32 v164, s76, v147
	v_add_u32_e32 v180, s77, v147
	ds_read_b128 v[152:155], v164
	ds_read_b128 v[156:159], v164 offset:1024
	ds_read_b128 v[160:163], v164 offset:2048
	ds_read_b128 v[164:167], v164 offset:3072
	ds_read_b128 v[168:171], v180
	ds_read_b128 v[172:175], v180 offset:1024
	ds_read_b128 v[176:179], v180 offset:2048
	ds_read_b128 v[180:183], v180 offset:3072
	s_add_u32 s48, s48, 0x40000
	s_addc_u32 s49, s49, 0
	s_mov_b32 m0, s57
	v_lshl_add_u64 v[226:227], s[48:49], 0, v[128:129]
	ds_read_b128 v[184:187], v151 offset:32768
	ds_read_b128 v[188:191], v151 offset:33792
	ds_read_b128 v[192:195], v151 offset:34816
	ds_read_b128 v[196:199], v151 offset:35840
	ds_read_b128 v[200:203], v151 offset:36864
	ds_read_b128 v[204:207], v151 offset:37888
	ds_read_b128 v[212:215], v151 offset:38912
	ds_read_b128 v[216:219], v151 offset:39936
	global_load_lds_dwordx4 v[226:227], off
	v_lshl_add_u64 v[226:227], s[48:49], 0, v[132:133]
	s_mov_b32 m0, s58
	s_nop 0
	global_load_lds_dwordx4 v[226:227], off
	s_waitcnt vmcnt(8)
	s_waitcnt lgkmcnt(0)
	s_setprio 1
	s_barrier
	v_mfma_f32_16x16x32_bf16 v[124:127], v[152:155], v[184:187], v[124:127]
	v_mfma_f32_16x16x32_bf16 v[120:123], v[160:163], v[184:187], v[120:123]
	v_mfma_f32_16x16x32_bf16 v[108:111], v[152:155], v[192:195], v[108:111]
	v_mfma_f32_16x16x32_bf16 v[104:107], v[160:163], v[192:195], v[104:107]
	v_mfma_f32_16x16x32_bf16 v[92:95], v[152:155], v[200:203], v[92:95]
	v_mfma_f32_16x16x32_bf16 v[88:91], v[160:163], v[200:203], v[88:91]
	v_mfma_f32_16x16x32_bf16 v[76:79], v[152:155], v[212:215], v[76:79]
	v_mfma_f32_16x16x32_bf16 v[72:75], v[160:163], v[212:215], v[72:75]
	v_mfma_f32_16x16x32_bf16 v[124:127], v[156:159], v[188:191], v[124:127]
	v_mfma_f32_16x16x32_bf16 v[120:123], v[164:167], v[188:191], v[120:123]
	v_mfma_f32_16x16x32_bf16 v[108:111], v[156:159], v[196:199], v[108:111]
	v_mfma_f32_16x16x32_bf16 v[104:107], v[164:167], v[196:199], v[104:107]
	v_mfma_f32_16x16x32_bf16 v[92:95], v[156:159], v[204:207], v[92:95]
	v_mfma_f32_16x16x32_bf16 v[88:91], v[164:167], v[204:207], v[88:91]
	v_mfma_f32_16x16x32_bf16 v[76:79], v[156:159], v[216:219], v[76:79]
	v_mfma_f32_16x16x32_bf16 v[72:75], v[164:167], v[216:219], v[72:75]
	s_setprio 0
	s_setprio 1
	v_mfma_f32_16x16x32_bf16 v[116:119], v[168:171], v[184:187], v[116:119]
	v_mfma_f32_16x16x32_bf16 v[112:115], v[176:179], v[184:187], v[112:115]
	v_mfma_f32_16x16x32_bf16 v[100:103], v[168:171], v[192:195], v[100:103]
	v_mfma_f32_16x16x32_bf16 v[96:99], v[176:179], v[192:195], v[96:99]
	v_mfma_f32_16x16x32_bf16 v[84:87], v[168:171], v[200:203], v[84:87]
	v_mfma_f32_16x16x32_bf16 v[80:83], v[176:179], v[200:203], v[80:83]
	v_mfma_f32_16x16x32_bf16 v[68:71], v[168:171], v[212:215], v[68:71]
	v_mfma_f32_16x16x32_bf16 v[64:67], v[176:179], v[212:215], v[64:67]
	v_mfma_f32_16x16x32_bf16 v[116:119], v[172:175], v[188:191], v[116:119]
	v_mfma_f32_16x16x32_bf16 v[112:115], v[180:183], v[188:191], v[112:115]
	v_mfma_f32_16x16x32_bf16 v[100:103], v[172:175], v[196:199], v[100:103]
	v_mfma_f32_16x16x32_bf16 v[96:99], v[180:183], v[196:199], v[96:99]
	v_mfma_f32_16x16x32_bf16 v[84:87], v[172:175], v[204:207], v[84:87]
	v_mfma_f32_16x16x32_bf16 v[80:83], v[180:183], v[204:207], v[80:83]
	v_mfma_f32_16x16x32_bf16 v[68:71], v[172:175], v[216:219], v[68:71]
	v_mfma_f32_16x16x32_bf16 v[64:67], v[180:183], v[216:219], v[64:67]
	s_setprio 0
	s_barrier
	s_add_i32 s48, s76, s55
	v_lshl_add_u64 v[144:145], v[144:145], 0, s[12:13]
	s_mov_b32 m0, s48
	ds_read_b128 v[184:187], v151 offset:49152
	ds_read_b128 v[188:191], v151 offset:50176
	ds_read_b128 v[192:195], v151 offset:51200
	ds_read_b128 v[196:199], v151 offset:52224
	ds_read_b128 v[200:203], v151 offset:53248
	ds_read_b128 v[204:207], v151 offset:54272
	ds_read_b128 v[212:215], v151 offset:55296
	ds_read_b128 v[216:219], v151 offset:56320
	global_load_lds_dwordx4 v[144:145], off
	s_add_i32 m0, s48, 0x2000
	s_add_u32 s46, s46, 0x40080
	v_lshl_add_u64 v[144:145], v[220:221], 0, s[12:13]
	s_addc_u32 s47, s47, 0
	s_add_i32 s48, s77, s55
	global_load_lds_dwordx4 v[144:145], off
	v_lshl_add_u64 v[144:145], s[46:47], 0, v[130:131]
	s_mov_b32 m0, s48
	s_nop 0
	global_load_lds_dwordx4 v[144:145], off
	v_lshl_add_u64 v[144:145], s[46:47], 0, v[134:135]
	s_add_i32 m0, s48, 0x2000
	s_nop 0
	global_load_lds_dwordx4 v[144:145], off
	v_lshl_add_u64 v[144:145], v[222:223], 0, s[12:13]
	s_mov_b32 m0, s60
	s_nop 0
	global_load_lds_dwordx4 v[144:145], off
	v_lshl_add_u64 v[144:145], v[224:225], 0, s[12:13]
	s_mov_b32 m0, s61
	s_nop 0
	global_load_lds_dwordx4 v[144:145], off
	s_waitcnt vmcnt(8)
	s_waitcnt lgkmcnt(0)
	s_setprio 1
	s_barrier
	v_mfma_f32_16x16x32_bf16 v[60:63], v[152:155], v[184:187], v[60:63]
	v_mfma_f32_16x16x32_bf16 v[56:59], v[160:163], v[184:187], v[56:59]
	v_mfma_f32_16x16x32_bf16 v[44:47], v[152:155], v[192:195], v[44:47]
	v_mfma_f32_16x16x32_bf16 v[40:43], v[160:163], v[192:195], v[40:43]
	v_mfma_f32_16x16x32_bf16 v[28:31], v[152:155], v[200:203], v[28:31]
	v_mfma_f32_16x16x32_bf16 v[24:27], v[160:163], v[200:203], v[24:27]
	v_mfma_f32_16x16x32_bf16 v[12:15], v[152:155], v[212:215], v[12:15]
	v_mfma_f32_16x16x32_bf16 v[8:11], v[160:163], v[212:215], v[8:11]
	v_mfma_f32_16x16x32_bf16 v[60:63], v[156:159], v[188:191], v[60:63]
	v_mfma_f32_16x16x32_bf16 v[56:59], v[164:167], v[188:191], v[56:59]
	v_mfma_f32_16x16x32_bf16 v[44:47], v[156:159], v[196:199], v[44:47]
	v_mfma_f32_16x16x32_bf16 v[40:43], v[164:167], v[196:199], v[40:43]
	v_mfma_f32_16x16x32_bf16 v[28:31], v[156:159], v[204:207], v[28:31]
	v_mfma_f32_16x16x32_bf16 v[24:27], v[164:167], v[204:207], v[24:27]
	v_mfma_f32_16x16x32_bf16 v[12:15], v[156:159], v[216:219], v[12:15]
	v_mfma_f32_16x16x32_bf16 v[8:11], v[164:167], v[216:219], v[8:11]
	s_setprio 0
	s_setprio 1
	v_mfma_f32_16x16x32_bf16 v[52:55], v[168:171], v[184:187], v[52:55]
	v_mfma_f32_16x16x32_bf16 v[48:51], v[176:179], v[184:187], v[48:51]
	v_mfma_f32_16x16x32_bf16 v[36:39], v[168:171], v[192:195], v[36:39]
	v_mfma_f32_16x16x32_bf16 v[32:35], v[176:179], v[192:195], v[32:35]
	v_mfma_f32_16x16x32_bf16 v[20:23], v[168:171], v[200:203], v[20:23]
	v_mfma_f32_16x16x32_bf16 v[16:19], v[176:179], v[200:203], v[16:19]
	v_mfma_f32_16x16x32_bf16 v[4:7], v[168:171], v[212:215], v[4:7]
	v_mfma_f32_16x16x32_bf16 v[0:3], v[176:179], v[212:215], v[0:3]
	s_add_i32 s75, s75, 2
	s_add_u32 s44, s44, 0x100
	s_addc_u32 s45, s45, 0
	s_add_u32 s73, s73, 0x100
	s_addc_u32 s74, s74, 0
	s_cmp_gt_u32 s75, 13
	v_mfma_f32_16x16x32_bf16 v[52:55], v[172:175], v[188:191], v[52:55]
	v_mfma_f32_16x16x32_bf16 v[48:51], v[180:183], v[188:191], v[48:51]
	v_mfma_f32_16x16x32_bf16 v[36:39], v[172:175], v[196:199], v[36:39]
	v_mfma_f32_16x16x32_bf16 v[32:35], v[180:183], v[196:199], v[32:35]
	v_mfma_f32_16x16x32_bf16 v[20:23], v[172:175], v[204:207], v[20:23]
	v_mfma_f32_16x16x32_bf16 v[16:19], v[180:183], v[204:207], v[16:19]
	v_mfma_f32_16x16x32_bf16 v[4:7], v[172:175], v[216:219], v[4:7]
	v_mfma_f32_16x16x32_bf16 v[0:3], v[180:183], v[216:219], v[0:3]
	s_setprio 0
	s_barrier
	s_cbranch_scc0 .LBB0_702
	s_and_b64 vcc, exec, s[14:15]
	s_cbranch_vccz .LBB0_705
	s_barrier

.LBB0_783:
	ds_read_b128 v[144:147], v154
	ds_read_b128 v[158:161], v154 offset:1024
	ds_read_b128 v[162:165], v154 offset:2048
	ds_read_b128 v[166:169], v154 offset:3072
	ds_read_b128 v[170:173], v155
	ds_read_b128 v[174:177], v155 offset:1024
	ds_read_b128 v[178:181], v155 offset:2048
	ds_read_b128 v[182:185], v155 offset:3072
	s_add_u32 s50, s48, 0xfff00080
	s_addc_u32 s51, s49, -1
	s_cmp_eq_u32 s73, 60
	s_cselect_b32 s53, s9, s51
	s_cselect_b32 s52, s41, s50
	s_cselect_b32 s51, s39, s72
	s_cselect_b32 s50, s47, s71
	v_lshl_add_u64 v[148:149], s[48:49], 0, v[136:137]
	s_add_i32 m0, s59, 0xc000
	ds_read_b128 v[186:189], v156
	ds_read_b128 v[190:193], v156 offset:1024
	ds_read_b128 v[194:197], v156 offset:2048
	ds_read_b128 v[198:201], v156 offset:3072
	ds_read_b128 v[202:205], v156 offset:4096
	ds_read_b128 v[212:215], v156 offset:5120
	ds_read_b128 v[216:219], v156 offset:6144
	ds_read_b128 v[220:223], v156 offset:7168
	global_load_lds_dwordx4 v[148:149], off
	v_lshl_add_u64 v[148:149], s[48:49], 0, v[138:139]
	s_add_i32 m0, s59, 0xe000
	s_nop 0
	global_load_lds_dwordx4 v[148:149], off
	s_waitcnt vmcnt(8)
	s_waitcnt lgkmcnt(0)
	s_setprio 1
	s_barrier
	v_mfma_f32_16x16x32_bf16 v[124:127], v[144:147], v[186:189], v[124:127]
	v_mfma_f32_16x16x32_bf16 v[120:123], v[162:165], v[186:189], v[120:123]
	v_mfma_f32_16x16x32_bf16 v[108:111], v[144:147], v[194:197], v[108:111]
	v_mfma_f32_16x16x32_bf16 v[104:107], v[162:165], v[194:197], v[104:107]
	v_mfma_f32_16x16x32_bf16 v[92:95], v[144:147], v[202:205], v[92:95]
	v_mfma_f32_16x16x32_bf16 v[88:91], v[162:165], v[202:205], v[88:91]
	v_mfma_f32_16x16x32_bf16 v[76:79], v[144:147], v[216:219], v[76:79]
	v_mfma_f32_16x16x32_bf16 v[72:75], v[162:165], v[216:219], v[72:75]
	v_mfma_f32_16x16x32_bf16 v[124:127], v[158:161], v[190:193], v[124:127]
	v_mfma_f32_16x16x32_bf16 v[120:123], v[166:169], v[190:193], v[120:123]
	v_mfma_f32_16x16x32_bf16 v[108:111], v[158:161], v[198:201], v[108:111]
	v_mfma_f32_16x16x32_bf16 v[104:107], v[166:169], v[198:201], v[104:107]
	v_mfma_f32_16x16x32_bf16 v[92:95], v[158:161], v[212:215], v[92:95]
	v_mfma_f32_16x16x32_bf16 v[88:91], v[166:169], v[212:215], v[88:91]
	v_mfma_f32_16x16x32_bf16 v[76:79], v[158:161], v[220:223], v[76:79]
	v_mfma_f32_16x16x32_bf16 v[72:75], v[166:169], v[220:223], v[72:75]
	s_setprio 0
	s_setprio 1
	v_mfma_f32_16x16x32_bf16 v[116:119], v[170:173], v[186:189], v[116:119]
	v_mfma_f32_16x16x32_bf16 v[112:115], v[178:181], v[186:189], v[112:115]
	v_mfma_f32_16x16x32_bf16 v[100:103], v[170:173], v[194:197], v[100:103]
	v_mfma_f32_16x16x32_bf16 v[96:99], v[178:181], v[194:197], v[96:99]
	v_mfma_f32_16x16x32_bf16 v[84:87], v[170:173], v[202:205], v[84:87]
	v_mfma_f32_16x16x32_bf16 v[80:83], v[178:181], v[202:205], v[80:83]
	v_mfma_f32_16x16x32_bf16 v[68:71], v[170:173], v[216:219], v[68:71]
	v_mfma_f32_16x16x32_bf16 v[64:67], v[178:181], v[216:219], v[64:67]
	v_mfma_f32_16x16x32_bf16 v[116:119], v[174:177], v[190:193], v[116:119]
	v_mfma_f32_16x16x32_bf16 v[112:115], v[182:185], v[190:193], v[112:115]
	v_mfma_f32_16x16x32_bf16 v[100:103], v[174:177], v[198:201], v[100:103]
	v_mfma_f32_16x16x32_bf16 v[96:99], v[182:185], v[198:201], v[96:99]
	v_mfma_f32_16x16x32_bf16 v[84:87], v[174:177], v[212:215], v[84:87]
	v_mfma_f32_16x16x32_bf16 v[80:83], v[182:185], v[212:215], v[80:83]
	v_mfma_f32_16x16x32_bf16 v[68:71], v[174:177], v[220:223], v[68:71]
	v_mfma_f32_16x16x32_bf16 v[64:67], v[182:185], v[220:223], v[64:67]
	s_setprio 0
	s_barrier
	s_add_i32 s74, s69, s58
	v_lshl_add_u64 v[148:149], s[50:51], 0, v[130:131]
	s_mov_b32 m0, s74
	ds_read_b128 v[186:189], v156 offset:16384
	ds_read_b128 v[190:193], v156 offset:17408
	ds_read_b128 v[194:197], v156 offset:18432
	ds_read_b128 v[198:201], v156 offset:19456
	ds_read_b128 v[202:205], v156 offset:20480
	ds_read_b128 v[212:215], v156 offset:21504
	ds_read_b128 v[216:219], v156 offset:22528
	ds_read_b128 v[220:223], v156 offset:23552
	global_load_lds_dwordx4 v[148:149], off
	s_add_i32 m0, s74, 0x2000
	s_add_u32 s74, s50, 0x100000
	v_lshl_add_u64 v[206:207], s[50:51], 0, v[134:135]
	s_addc_u32 s75, s51, 0
	s_add_i32 s76, s70, s58
	global_load_lds_dwordx4 v[206:207], off
	v_lshl_add_u64 v[224:225], s[74:75], 0, v[130:131]
	s_mov_b32 m0, s76
	v_lshl_add_u64 v[226:227], s[52:53], 0, v[132:133]
	global_load_lds_dwordx4 v[224:225], off
	v_lshl_add_u64 v[224:225], s[74:75], 0, v[134:135]
	s_add_i32 m0, s76, 0x2000
	s_nop 0
	global_load_lds_dwordx4 v[224:225], off
	v_lshl_add_u64 v[224:225], s[52:53], 0, v[128:129]
	s_mov_b32 m0, s59
	s_nop 0
	global_load_lds_dwordx4 v[224:225], off
	s_mov_b32 m0, s60
	s_nop 0
	global_load_lds_dwordx4 v[226:227], off
	s_waitcnt vmcnt(8)
	s_waitcnt lgkmcnt(0)
	s_setprio 1
	s_barrier
	v_mfma_f32_16x16x32_bf16 v[60:63], v[144:147], v[186:189], v[60:63]
	v_mfma_f32_16x16x32_bf16 v[56:59], v[162:165], v[186:189], v[56:59]
	v_mfma_f32_16x16x32_bf16 v[44:47], v[144:147], v[194:197], v[44:47]
	v_mfma_f32_16x16x32_bf16 v[40:43], v[162:165], v[194:197], v[40:43]
	v_mfma_f32_16x16x32_bf16 v[28:31], v[144:147], v[202:205], v[28:31]
	v_mfma_f32_16x16x32_bf16 v[24:27], v[162:165], v[202:205], v[24:27]
	v_mfma_f32_16x16x32_bf16 v[12:15], v[144:147], v[216:219], v[12:15]
	v_mfma_f32_16x16x32_bf16 v[8:11], v[162:165], v[216:219], v[8:11]
	v_mfma_f32_16x16x32_bf16 v[60:63], v[158:161], v[190:193], v[60:63]
	v_mfma_f32_16x16x32_bf16 v[56:59], v[166:169], v[190:193], v[56:59]
	v_mfma_f32_16x16x32_bf16 v[44:47], v[158:161], v[198:201], v[44:47]
	v_mfma_f32_16x16x32_bf16 v[40:43], v[166:169], v[198:201], v[40:43]
	v_mfma_f32_16x16x32_bf16 v[28:31], v[158:161], v[212:215], v[28:31]
	v_mfma_f32_16x16x32_bf16 v[24:27], v[166:169], v[212:215], v[24:27]
	v_mfma_f32_16x16x32_bf16 v[12:15], v[158:161], v[220:223], v[12:15]
	v_mfma_f32_16x16x32_bf16 v[8:11], v[166:169], v[220:223], v[8:11]
	s_setprio 0
	s_setprio 1
	v_mfma_f32_16x16x32_bf16 v[52:55], v[170:173], v[186:189], v[52:55]
	v_mfma_f32_16x16x32_bf16 v[48:51], v[178:181], v[186:189], v[48:51]
	v_mfma_f32_16x16x32_bf16 v[36:39], v[170:173], v[194:197], v[36:39]
	v_mfma_f32_16x16x32_bf16 v[32:35], v[178:181], v[194:197], v[32:35]
	v_mfma_f32_16x16x32_bf16 v[20:23], v[170:173], v[202:205], v[20:23]
	v_mfma_f32_16x16x32_bf16 v[16:19], v[178:181], v[202:205], v[16:19]
	v_mfma_f32_16x16x32_bf16 v[4:7], v[170:173], v[216:219], v[4:7]
	v_mfma_f32_16x16x32_bf16 v[0:3], v[178:181], v[216:219], v[0:3]
	v_mfma_f32_16x16x32_bf16 v[52:55], v[174:177], v[190:193], v[52:55]
	v_mfma_f32_16x16x32_bf16 v[48:51], v[182:185], v[190:193], v[48:51]
	v_mfma_f32_16x16x32_bf16 v[36:39], v[174:177], v[198:201], v[36:39]
	v_mfma_f32_16x16x32_bf16 v[32:35], v[182:185], v[198:201], v[32:35]
	v_mfma_f32_16x16x32_bf16 v[20:23], v[174:177], v[212:215], v[20:23]
	v_mfma_f32_16x16x32_bf16 v[16:19], v[182:185], v[212:215], v[16:19]
	v_mfma_f32_16x16x32_bf16 v[4:7], v[174:177], v[220:223], v[4:7]
	v_mfma_f32_16x16x32_bf16 v[0:3], v[182:185], v[220:223], v[0:3]
	s_setprio 0
	s_barrier
	s_add_i32 s74, 0, 0x18000
	v_add_u32_e32 v150, s74, v152
	s_add_i32 s75, 0, 0x1c000
	ds_read_b128 v[144:147], v150
	ds_read_b128 v[158:161], v150 offset:1024
	ds_read_b128 v[162:165], v150 offset:2048
	ds_read_b128 v[166:169], v150 offset:3072
	v_add_u32_e32 v150, s75, v152
	ds_read_b128 v[170:173], v150
	ds_read_b128 v[174:177], v150 offset:1024
	ds_read_b128 v[178:181], v150 offset:2048
	ds_read_b128 v[182:185], v150 offset:3072
	s_add_u32 s52, s52, 0x100000
	s_addc_u32 s53, s53, 0
	s_mov_b32 m0, s61
	v_lshl_add_u64 v[228:229], s[52:53], 0, v[128:129]
	ds_read_b128 v[186:189], v156 offset:32768
	ds_read_b128 v[190:193], v156 offset:33792
	ds_read_b128 v[194:197], v156 offset:34816
	ds_read_b128 v[198:201], v156 offset:35840
	ds_read_b128 v[202:205], v156 offset:36864
	ds_read_b128 v[212:215], v156 offset:37888
	ds_read_b128 v[216:219], v156 offset:38912
	ds_read_b128 v[220:223], v156 offset:39936
	global_load_lds_dwordx4 v[228:229], off
	v_lshl_add_u64 v[228:229], s[52:53], 0, v[132:133]
	s_mov_b32 m0, s62
	s_nop 0
	global_load_lds_dwordx4 v[228:229], off
	s_waitcnt vmcnt(8)
	s_waitcnt lgkmcnt(0)
	s_setprio 1
	s_barrier
	v_mfma_f32_16x16x32_bf16 v[124:127], v[144:147], v[186:189], v[124:127]
	v_mfma_f32_16x16x32_bf16 v[120:123], v[162:165], v[186:189], v[120:123]
	v_mfma_f32_16x16x32_bf16 v[108:111], v[144:147], v[194:197], v[108:111]
	v_mfma_f32_16x16x32_bf16 v[104:107], v[162:165], v[194:197], v[104:107]
	v_mfma_f32_16x16x32_bf16 v[92:95], v[144:147], v[202:205], v[92:95]
	v_mfma_f32_16x16x32_bf16 v[88:91], v[162:165], v[202:205], v[88:91]
	v_mfma_f32_16x16x32_bf16 v[76:79], v[144:147], v[216:219], v[76:79]
	v_mfma_f32_16x16x32_bf16 v[72:75], v[162:165], v[216:219], v[72:75]
	v_mfma_f32_16x16x32_bf16 v[124:127], v[158:161], v[190:193], v[124:127]
	v_mfma_f32_16x16x32_bf16 v[120:123], v[166:169], v[190:193], v[120:123]
	v_mfma_f32_16x16x32_bf16 v[108:111], v[158:161], v[198:201], v[108:111]
	v_mfma_f32_16x16x32_bf16 v[104:107], v[166:169], v[198:201], v[104:107]
	v_mfma_f32_16x16x32_bf16 v[92:95], v[158:161], v[212:215], v[92:95]
	v_mfma_f32_16x16x32_bf16 v[88:91], v[166:169], v[212:215], v[88:91]
	v_mfma_f32_16x16x32_bf16 v[76:79], v[158:161], v[220:223], v[76:79]
	v_mfma_f32_16x16x32_bf16 v[72:75], v[166:169], v[220:223], v[72:75]
	s_setprio 0
	s_setprio 1
	v_mfma_f32_16x16x32_bf16 v[116:119], v[170:173], v[186:189], v[116:119]
	v_mfma_f32_16x16x32_bf16 v[112:115], v[178:181], v[186:189], v[112:115]
	v_mfma_f32_16x16x32_bf16 v[100:103], v[170:173], v[194:197], v[100:103]
	v_mfma_f32_16x16x32_bf16 v[96:99], v[178:181], v[194:197], v[96:99]
	v_mfma_f32_16x16x32_bf16 v[84:87], v[170:173], v[202:205], v[84:87]
	v_mfma_f32_16x16x32_bf16 v[80:83], v[178:181], v[202:205], v[80:83]
	v_mfma_f32_16x16x32_bf16 v[68:71], v[170:173], v[216:219], v[68:71]
	v_mfma_f32_16x16x32_bf16 v[64:67], v[178:181], v[216:219], v[64:67]
	v_mfma_f32_16x16x32_bf16 v[116:119], v[174:177], v[190:193], v[116:119]
	v_mfma_f32_16x16x32_bf16 v[112:115], v[182:185], v[190:193], v[112:115]
	v_mfma_f32_16x16x32_bf16 v[100:103], v[174:177], v[198:201], v[100:103]
	v_mfma_f32_16x16x32_bf16 v[96:99], v[182:185], v[198:201], v[96:99]
	v_mfma_f32_16x16x32_bf16 v[84:87], v[174:177], v[212:215], v[84:87]
	v_mfma_f32_16x16x32_bf16 v[80:83], v[182:185], v[212:215], v[80:83]
	v_mfma_f32_16x16x32_bf16 v[68:71], v[174:177], v[220:223], v[68:71]
	v_mfma_f32_16x16x32_bf16 v[64:67], v[182:185], v[220:223], v[64:67]
	s_setprio 0
	s_barrier
	s_add_i32 s52, s74, s58
	v_lshl_add_u64 v[148:149], v[148:149], 0, s[22:23]
	s_mov_b32 m0, s52
	ds_read_b128 v[186:189], v156 offset:49152
	ds_read_b128 v[190:193], v156 offset:50176
	ds_read_b128 v[194:197], v156 offset:51200
	ds_read_b128 v[198:201], v156 offset:52224
	ds_read_b128 v[202:205], v156 offset:53248
	ds_read_b128 v[212:215], v156 offset:54272
	ds_read_b128 v[216:219], v156 offset:55296
	ds_read_b128 v[220:223], v156 offset:56320
	global_load_lds_dwordx4 v[148:149], off
	s_add_i32 m0, s52, 0x2000
	s_add_u32 s50, s50, 0x100080
	v_lshl_add_u64 v[148:149], v[206:207], 0, s[22:23]
	s_addc_u32 s51, s51, 0
	s_add_i32 s52, s75, s58
	global_load_lds_dwordx4 v[148:149], off
	v_lshl_add_u64 v[148:149], s[50:51], 0, v[130:131]
	s_mov_b32 m0, s52
	s_nop 0
	global_load_lds_dwordx4 v[148:149], off
	v_lshl_add_u64 v[148:149], s[50:51], 0, v[134:135]
	s_add_i32 m0, s52, 0x2000
	s_nop 0
	global_load_lds_dwordx4 v[148:149], off
	v_lshl_add_u64 v[148:149], v[224:225], 0, s[22:23]
	s_mov_b32 m0, s64
	s_nop 0
	global_load_lds_dwordx4 v[148:149], off
	v_lshl_add_u64 v[148:149], v[226:227], 0, s[22:23]
	s_mov_b32 m0, s65
	s_nop 0
	global_load_lds_dwordx4 v[148:149], off
	s_waitcnt vmcnt(8)
	s_waitcnt lgkmcnt(0)
	s_setprio 1
	s_barrier
	v_mfma_f32_16x16x32_bf16 v[60:63], v[144:147], v[186:189], v[60:63]
	v_mfma_f32_16x16x32_bf16 v[56:59], v[162:165], v[186:189], v[56:59]
	v_mfma_f32_16x16x32_bf16 v[44:47], v[144:147], v[194:197], v[44:47]
	v_mfma_f32_16x16x32_bf16 v[40:43], v[162:165], v[194:197], v[40:43]
	v_mfma_f32_16x16x32_bf16 v[28:31], v[144:147], v[202:205], v[28:31]
	v_mfma_f32_16x16x32_bf16 v[24:27], v[162:165], v[202:205], v[24:27]
	v_mfma_f32_16x16x32_bf16 v[12:15], v[144:147], v[216:219], v[12:15]
	v_mfma_f32_16x16x32_bf16 v[8:11], v[162:165], v[216:219], v[8:11]
	v_mfma_f32_16x16x32_bf16 v[60:63], v[158:161], v[190:193], v[60:63]
	v_mfma_f32_16x16x32_bf16 v[56:59], v[166:169], v[190:193], v[56:59]
	v_mfma_f32_16x16x32_bf16 v[44:47], v[158:161], v[198:201], v[44:47]
	v_mfma_f32_16x16x32_bf16 v[40:43], v[166:169], v[198:201], v[40:43]
	v_mfma_f32_16x16x32_bf16 v[28:31], v[158:161], v[212:215], v[28:31]
	v_mfma_f32_16x16x32_bf16 v[24:27], v[166:169], v[212:215], v[24:27]
	v_mfma_f32_16x16x32_bf16 v[12:15], v[158:161], v[220:223], v[12:15]
	v_mfma_f32_16x16x32_bf16 v[8:11], v[166:169], v[220:223], v[8:11]
	s_setprio 0
	s_setprio 1
	v_mfma_f32_16x16x32_bf16 v[52:55], v[170:173], v[186:189], v[52:55]
	v_mfma_f32_16x16x32_bf16 v[48:51], v[178:181], v[186:189], v[48:51]
	v_mfma_f32_16x16x32_bf16 v[36:39], v[170:173], v[194:197], v[36:39]
	v_mfma_f32_16x16x32_bf16 v[32:35], v[178:181], v[194:197], v[32:35]
	v_mfma_f32_16x16x32_bf16 v[20:23], v[170:173], v[202:205], v[20:23]
	v_mfma_f32_16x16x32_bf16 v[16:19], v[178:181], v[202:205], v[16:19]
	v_mfma_f32_16x16x32_bf16 v[4:7], v[170:173], v[216:219], v[4:7]
	v_mfma_f32_16x16x32_bf16 v[0:3], v[178:181], v[216:219], v[0:3]
	s_add_i32 s73, s73, 2
	s_add_u32 s48, s48, 0x100
	s_addc_u32 s49, s49, 0
	s_add_u32 s71, s71, 0x100
	s_addc_u32 s72, s72, 0
	s_cmp_gt_u32 s73, 61
	v_mfma_f32_16x16x32_bf16 v[52:55], v[174:177], v[190:193], v[52:55]
	v_mfma_f32_16x16x32_bf16 v[48:51], v[182:185], v[190:193], v[48:51]
	v_mfma_f32_16x16x32_bf16 v[36:39], v[174:177], v[198:201], v[36:39]
	v_mfma_f32_16x16x32_bf16 v[32:35], v[182:185], v[198:201], v[32:35]
	v_mfma_f32_16x16x32_bf16 v[20:23], v[174:177], v[212:215], v[20:23]
	v_mfma_f32_16x16x32_bf16 v[16:19], v[182:185], v[212:215], v[16:19]
	v_mfma_f32_16x16x32_bf16 v[4:7], v[174:177], v[220:223], v[4:7]
	v_mfma_f32_16x16x32_bf16 v[0:3], v[182:185], v[220:223], v[0:3]
	s_setprio 0
	s_barrier
	s_cbranch_scc0 .LBB0_783
	s_and_b64 vcc, exec, s[24:25]
	s_cbranch_vccz .LBB0_786
	s_barrier

.LBB0_902:
	ds_read_b128 v[146:149], v152
	ds_read_b128 v[158:161], v152 offset:1024
	ds_read_b128 v[162:165], v152 offset:2048
	ds_read_b128 v[166:169], v152 offset:3072
	ds_read_b128 v[170:173], v153
	ds_read_b128 v[174:177], v153 offset:1024
	ds_read_b128 v[178:181], v153 offset:2048
	ds_read_b128 v[182:185], v153 offset:3072
	s_add_u32 s38, s36, 0xfffc0080
	s_addc_u32 s39, s37, -1
	s_cmp_eq_u32 s65, 12
	s_cselect_b32 s41, s19, s39
	s_cselect_b32 s40, s61, s38
	s_cselect_b32 s39, s17, s64
	s_cselect_b32 s38, s62, s63
	v_lshl_add_u64 v[206:207], s[36:37], 0, v[138:139]
	s_add_i32 m0, s25, 0xc000
	ds_read_b128 v[186:189], v154
	ds_read_b128 v[190:193], v154 offset:1024
	ds_read_b128 v[194:197], v154 offset:2048
	ds_read_b128 v[198:201], v154 offset:3072
	ds_read_b128 v[202:205], v154 offset:4096
	ds_read_b128 v[212:215], v154 offset:5120
	ds_read_b128 v[216:219], v154 offset:6144
	ds_read_b128 v[220:223], v154 offset:7168
	global_load_lds_dwordx4 v[206:207], off
	v_lshl_add_u64 v[206:207], s[36:37], 0, v[140:141]
	s_add_i32 m0, s25, 0xe000
	s_nop 0
	global_load_lds_dwordx4 v[206:207], off
	s_waitcnt vmcnt(8)
	s_waitcnt lgkmcnt(0)
	s_setprio 1
	s_barrier
	v_mfma_f32_16x16x32_bf16 v[124:127], v[146:149], v[186:189], v[124:127]
	v_mfma_f32_16x16x32_bf16 v[120:123], v[162:165], v[186:189], v[120:123]
	v_mfma_f32_16x16x32_bf16 v[108:111], v[146:149], v[194:197], v[108:111]
	v_mfma_f32_16x16x32_bf16 v[104:107], v[162:165], v[194:197], v[104:107]
	v_mfma_f32_16x16x32_bf16 v[92:95], v[146:149], v[202:205], v[92:95]
	v_mfma_f32_16x16x32_bf16 v[88:91], v[162:165], v[202:205], v[88:91]
	v_mfma_f32_16x16x32_bf16 v[76:79], v[146:149], v[216:219], v[76:79]
	v_mfma_f32_16x16x32_bf16 v[72:75], v[162:165], v[216:219], v[72:75]
	v_mfma_f32_16x16x32_bf16 v[124:127], v[158:161], v[190:193], v[124:127]
	v_mfma_f32_16x16x32_bf16 v[120:123], v[166:169], v[190:193], v[120:123]
	v_mfma_f32_16x16x32_bf16 v[108:111], v[158:161], v[198:201], v[108:111]
	v_mfma_f32_16x16x32_bf16 v[104:107], v[166:169], v[198:201], v[104:107]
	v_mfma_f32_16x16x32_bf16 v[92:95], v[158:161], v[212:215], v[92:95]
	v_mfma_f32_16x16x32_bf16 v[88:91], v[166:169], v[212:215], v[88:91]
	v_mfma_f32_16x16x32_bf16 v[76:79], v[158:161], v[220:223], v[76:79]
	v_mfma_f32_16x16x32_bf16 v[72:75], v[166:169], v[220:223], v[72:75]
	s_setprio 0
	s_setprio 1
	v_mfma_f32_16x16x32_bf16 v[116:119], v[170:173], v[186:189], v[116:119]
	v_mfma_f32_16x16x32_bf16 v[112:115], v[178:181], v[186:189], v[112:115]
	v_mfma_f32_16x16x32_bf16 v[100:103], v[170:173], v[194:197], v[100:103]
	v_mfma_f32_16x16x32_bf16 v[96:99], v[178:181], v[194:197], v[96:99]
	v_mfma_f32_16x16x32_bf16 v[84:87], v[170:173], v[202:205], v[84:87]
	v_mfma_f32_16x16x32_bf16 v[80:83], v[178:181], v[202:205], v[80:83]
	v_mfma_f32_16x16x32_bf16 v[68:71], v[170:173], v[216:219], v[68:71]
	v_mfma_f32_16x16x32_bf16 v[64:67], v[178:181], v[216:219], v[64:67]
	v_mfma_f32_16x16x32_bf16 v[116:119], v[174:177], v[190:193], v[116:119]
	v_mfma_f32_16x16x32_bf16 v[112:115], v[182:185], v[190:193], v[112:115]
	v_mfma_f32_16x16x32_bf16 v[100:103], v[174:177], v[198:201], v[100:103]
	v_mfma_f32_16x16x32_bf16 v[96:99], v[182:185], v[198:201], v[96:99]
	v_mfma_f32_16x16x32_bf16 v[84:87], v[174:177], v[212:215], v[84:87]
	v_mfma_f32_16x16x32_bf16 v[80:83], v[182:185], v[212:215], v[80:83]
	v_mfma_f32_16x16x32_bf16 v[68:71], v[174:177], v[220:223], v[68:71]
	v_mfma_f32_16x16x32_bf16 v[64:67], v[182:185], v[220:223], v[64:67]
	s_setprio 0
	s_barrier
	s_add_i32 s66, s57, s47
	v_lshl_add_u64 v[206:207], s[38:39], 0, v[130:131]
	s_mov_b32 m0, s66
	ds_read_b128 v[186:189], v154 offset:16384
	ds_read_b128 v[190:193], v154 offset:17408
	ds_read_b128 v[194:197], v154 offset:18432
	ds_read_b128 v[198:201], v154 offset:19456
	ds_read_b128 v[202:205], v154 offset:20480
	ds_read_b128 v[212:215], v154 offset:21504
	ds_read_b128 v[216:219], v154 offset:22528
	ds_read_b128 v[220:223], v154 offset:23552
	global_load_lds_dwordx4 v[206:207], off
	s_add_i32 m0, s66, 0x2000
	s_add_u32 s66, s38, 0x40000
	v_lshl_add_u64 v[224:225], s[38:39], 0, v[134:135]
	s_addc_u32 s67, s39, 0
	s_add_i32 s68, s58, s47
	global_load_lds_dwordx4 v[224:225], off
	v_lshl_add_u64 v[226:227], s[66:67], 0, v[130:131]
	s_mov_b32 m0, s68
	v_lshl_add_u64 v[228:229], s[40:41], 0, v[132:133]
	global_load_lds_dwordx4 v[226:227], off
	v_lshl_add_u64 v[226:227], s[66:67], 0, v[134:135]
	s_add_i32 m0, s68, 0x2000
	s_nop 0
	global_load_lds_dwordx4 v[226:227], off
	v_lshl_add_u64 v[226:227], s[40:41], 0, v[128:129]
	s_mov_b32 m0, s25
	s_nop 0
	global_load_lds_dwordx4 v[226:227], off
	s_mov_b32 m0, s48
	s_nop 0
	global_load_lds_dwordx4 v[228:229], off
	s_waitcnt vmcnt(8)
	s_waitcnt lgkmcnt(0)
	s_setprio 1
	s_barrier
	v_mfma_f32_16x16x32_bf16 v[60:63], v[146:149], v[186:189], v[60:63]
	v_mfma_f32_16x16x32_bf16 v[56:59], v[162:165], v[186:189], v[56:59]
	v_mfma_f32_16x16x32_bf16 v[44:47], v[146:149], v[194:197], v[44:47]
	v_mfma_f32_16x16x32_bf16 v[40:43], v[162:165], v[194:197], v[40:43]
	v_mfma_f32_16x16x32_bf16 v[28:31], v[146:149], v[202:205], v[28:31]
	v_mfma_f32_16x16x32_bf16 v[24:27], v[162:165], v[202:205], v[24:27]
	v_mfma_f32_16x16x32_bf16 v[12:15], v[146:149], v[216:219], v[12:15]
	v_mfma_f32_16x16x32_bf16 v[8:11], v[162:165], v[216:219], v[8:11]
	v_mfma_f32_16x16x32_bf16 v[60:63], v[158:161], v[190:193], v[60:63]
	v_mfma_f32_16x16x32_bf16 v[56:59], v[166:169], v[190:193], v[56:59]
	v_mfma_f32_16x16x32_bf16 v[44:47], v[158:161], v[198:201], v[44:47]
	v_mfma_f32_16x16x32_bf16 v[40:43], v[166:169], v[198:201], v[40:43]
	v_mfma_f32_16x16x32_bf16 v[28:31], v[158:161], v[212:215], v[28:31]
	v_mfma_f32_16x16x32_bf16 v[24:27], v[166:169], v[212:215], v[24:27]
	v_mfma_f32_16x16x32_bf16 v[12:15], v[158:161], v[220:223], v[12:15]
	v_mfma_f32_16x16x32_bf16 v[8:11], v[166:169], v[220:223], v[8:11]
	s_setprio 0
	s_setprio 1
	v_mfma_f32_16x16x32_bf16 v[52:55], v[170:173], v[186:189], v[52:55]
	v_mfma_f32_16x16x32_bf16 v[48:51], v[178:181], v[186:189], v[48:51]
	v_mfma_f32_16x16x32_bf16 v[36:39], v[170:173], v[194:197], v[36:39]
	v_mfma_f32_16x16x32_bf16 v[32:35], v[178:181], v[194:197], v[32:35]
	v_mfma_f32_16x16x32_bf16 v[20:23], v[170:173], v[202:205], v[20:23]
	v_mfma_f32_16x16x32_bf16 v[16:19], v[178:181], v[202:205], v[16:19]
	v_mfma_f32_16x16x32_bf16 v[4:7], v[170:173], v[216:219], v[4:7]
	v_mfma_f32_16x16x32_bf16 v[0:3], v[178:181], v[216:219], v[0:3]
	v_mfma_f32_16x16x32_bf16 v[52:55], v[174:177], v[190:193], v[52:55]
	v_mfma_f32_16x16x32_bf16 v[48:51], v[182:185], v[190:193], v[48:51]
	v_mfma_f32_16x16x32_bf16 v[36:39], v[174:177], v[198:201], v[36:39]
	v_mfma_f32_16x16x32_bf16 v[32:35], v[182:185], v[198:201], v[32:35]
	v_mfma_f32_16x16x32_bf16 v[20:23], v[174:177], v[212:215], v[20:23]
	v_mfma_f32_16x16x32_bf16 v[16:19], v[182:185], v[212:215], v[16:19]
	v_mfma_f32_16x16x32_bf16 v[4:7], v[174:177], v[220:223], v[4:7]
	v_mfma_f32_16x16x32_bf16 v[0:3], v[182:185], v[220:223], v[0:3]
	s_setprio 0
	s_barrier
	s_add_i32 s66, 0, 0x18000
	s_add_i32 s67, 0, 0x1c000
	v_add_u32_e32 v166, s66, v151
	v_add_u32_e32 v182, s67, v151
	ds_read_b128 v[146:149], v166
	ds_read_b128 v[158:161], v166 offset:1024
	ds_read_b128 v[162:165], v166 offset:2048
	ds_read_b128 v[166:169], v166 offset:3072
	ds_read_b128 v[170:173], v182
	ds_read_b128 v[174:177], v182 offset:1024
	ds_read_b128 v[178:181], v182 offset:2048
	ds_read_b128 v[182:185], v182 offset:3072
	s_add_u32 s40, s40, 0x40000
	s_addc_u32 s41, s41, 0
	s_mov_b32 m0, s49
	v_lshl_add_u64 v[230:231], s[40:41], 0, v[128:129]
	ds_read_b128 v[186:189], v154 offset:32768
	ds_read_b128 v[190:193], v154 offset:33792
	ds_read_b128 v[194:197], v154 offset:34816
	ds_read_b128 v[198:201], v154 offset:35840
	ds_read_b128 v[202:205], v154 offset:36864
	ds_read_b128 v[212:215], v154 offset:37888
	ds_read_b128 v[216:219], v154 offset:38912
	ds_read_b128 v[220:223], v154 offset:39936
	global_load_lds_dwordx4 v[230:231], off
	v_lshl_add_u64 v[230:231], s[40:41], 0, v[132:133]
	s_mov_b32 m0, s50
	s_nop 0
	global_load_lds_dwordx4 v[230:231], off
	s_waitcnt vmcnt(8)
	s_waitcnt lgkmcnt(0)
	s_setprio 1
	s_barrier
	v_mfma_f32_16x16x32_bf16 v[124:127], v[146:149], v[186:189], v[124:127]
	v_mfma_f32_16x16x32_bf16 v[120:123], v[162:165], v[186:189], v[120:123]
	v_mfma_f32_16x16x32_bf16 v[108:111], v[146:149], v[194:197], v[108:111]
	v_mfma_f32_16x16x32_bf16 v[104:107], v[162:165], v[194:197], v[104:107]
	v_mfma_f32_16x16x32_bf16 v[92:95], v[146:149], v[202:205], v[92:95]
	v_mfma_f32_16x16x32_bf16 v[88:91], v[162:165], v[202:205], v[88:91]
	v_mfma_f32_16x16x32_bf16 v[76:79], v[146:149], v[216:219], v[76:79]
	v_mfma_f32_16x16x32_bf16 v[72:75], v[162:165], v[216:219], v[72:75]
	v_mfma_f32_16x16x32_bf16 v[124:127], v[158:161], v[190:193], v[124:127]
	v_mfma_f32_16x16x32_bf16 v[120:123], v[166:169], v[190:193], v[120:123]
	v_mfma_f32_16x16x32_bf16 v[108:111], v[158:161], v[198:201], v[108:111]
	v_mfma_f32_16x16x32_bf16 v[104:107], v[166:169], v[198:201], v[104:107]
	v_mfma_f32_16x16x32_bf16 v[92:95], v[158:161], v[212:215], v[92:95]
	v_mfma_f32_16x16x32_bf16 v[88:91], v[166:169], v[212:215], v[88:91]
	v_mfma_f32_16x16x32_bf16 v[76:79], v[158:161], v[220:223], v[76:79]
	v_mfma_f32_16x16x32_bf16 v[72:75], v[166:169], v[220:223], v[72:75]
	s_setprio 0
	s_setprio 1
	v_mfma_f32_16x16x32_bf16 v[116:119], v[170:173], v[186:189], v[116:119]
	v_mfma_f32_16x16x32_bf16 v[112:115], v[178:181], v[186:189], v[112:115]
	v_mfma_f32_16x16x32_bf16 v[100:103], v[170:173], v[194:197], v[100:103]
	v_mfma_f32_16x16x32_bf16 v[96:99], v[178:181], v[194:197], v[96:99]
	v_mfma_f32_16x16x32_bf16 v[84:87], v[170:173], v[202:205], v[84:87]
	v_mfma_f32_16x16x32_bf16 v[80:83], v[178:181], v[202:205], v[80:83]
	v_mfma_f32_16x16x32_bf16 v[68:71], v[170:173], v[216:219], v[68:71]
	v_mfma_f32_16x16x32_bf16 v[64:67], v[178:181], v[216:219], v[64:67]
	v_mfma_f32_16x16x32_bf16 v[116:119], v[174:177], v[190:193], v[116:119]
	v_mfma_f32_16x16x32_bf16 v[112:115], v[182:185], v[190:193], v[112:115]
	v_mfma_f32_16x16x32_bf16 v[100:103], v[174:177], v[198:201], v[100:103]
	v_mfma_f32_16x16x32_bf16 v[96:99], v[182:185], v[198:201], v[96:99]
	v_mfma_f32_16x16x32_bf16 v[84:87], v[174:177], v[212:215], v[84:87]
	v_mfma_f32_16x16x32_bf16 v[80:83], v[182:185], v[212:215], v[80:83]
	v_mfma_f32_16x16x32_bf16 v[68:71], v[174:177], v[220:223], v[68:71]
	v_mfma_f32_16x16x32_bf16 v[64:67], v[182:185], v[220:223], v[64:67]
	s_setprio 0
	s_barrier
	s_add_i32 s40, s66, s47
	v_lshl_add_u64 v[206:207], v[206:207], 0, s[12:13]
	s_mov_b32 m0, s40
	ds_read_b128 v[186:189], v154 offset:49152
	ds_read_b128 v[190:193], v154 offset:50176
	ds_read_b128 v[194:197], v154 offset:51200
	ds_read_b128 v[198:201], v154 offset:52224
	ds_read_b128 v[202:205], v154 offset:53248
	ds_read_b128 v[212:215], v154 offset:54272
	ds_read_b128 v[216:219], v154 offset:55296
	ds_read_b128 v[220:223], v154 offset:56320
	global_load_lds_dwordx4 v[206:207], off
	s_add_i32 m0, s40, 0x2000
	s_add_u32 s38, s38, 0x40080
	v_lshl_add_u64 v[206:207], v[224:225], 0, s[12:13]
	s_addc_u32 s39, s39, 0
	s_add_i32 s40, s67, s47
	global_load_lds_dwordx4 v[206:207], off
	v_lshl_add_u64 v[206:207], s[38:39], 0, v[130:131]
	s_mov_b32 m0, s40
	s_nop 0
	global_load_lds_dwordx4 v[206:207], off
	v_lshl_add_u64 v[206:207], s[38:39], 0, v[134:135]
	s_add_i32 m0, s40, 0x2000
	s_nop 0
	global_load_lds_dwordx4 v[206:207], off
	v_lshl_add_u64 v[206:207], v[226:227], 0, s[12:13]
	s_mov_b32 m0, s53
	s_nop 0
	global_load_lds_dwordx4 v[206:207], off
	v_lshl_add_u64 v[206:207], v[228:229], 0, s[12:13]
	s_mov_b32 m0, s54
	s_nop 0
	global_load_lds_dwordx4 v[206:207], off
	s_waitcnt vmcnt(8)
	s_waitcnt lgkmcnt(0)
	s_setprio 1
	s_barrier
	v_mfma_f32_16x16x32_bf16 v[60:63], v[146:149], v[186:189], v[60:63]
	v_mfma_f32_16x16x32_bf16 v[56:59], v[162:165], v[186:189], v[56:59]
	v_mfma_f32_16x16x32_bf16 v[44:47], v[146:149], v[194:197], v[44:47]
	v_mfma_f32_16x16x32_bf16 v[40:43], v[162:165], v[194:197], v[40:43]
	v_mfma_f32_16x16x32_bf16 v[28:31], v[146:149], v[202:205], v[28:31]
	v_mfma_f32_16x16x32_bf16 v[24:27], v[162:165], v[202:205], v[24:27]
	v_mfma_f32_16x16x32_bf16 v[12:15], v[146:149], v[216:219], v[12:15]
	v_mfma_f32_16x16x32_bf16 v[8:11], v[162:165], v[216:219], v[8:11]
	v_mfma_f32_16x16x32_bf16 v[60:63], v[158:161], v[190:193], v[60:63]
	v_mfma_f32_16x16x32_bf16 v[56:59], v[166:169], v[190:193], v[56:59]
	v_mfma_f32_16x16x32_bf16 v[44:47], v[158:161], v[198:201], v[44:47]
	v_mfma_f32_16x16x32_bf16 v[40:43], v[166:169], v[198:201], v[40:43]
	v_mfma_f32_16x16x32_bf16 v[28:31], v[158:161], v[212:215], v[28:31]
	v_mfma_f32_16x16x32_bf16 v[24:27], v[166:169], v[212:215], v[24:27]
	v_mfma_f32_16x16x32_bf16 v[12:15], v[158:161], v[220:223], v[12:15]
	v_mfma_f32_16x16x32_bf16 v[8:11], v[166:169], v[220:223], v[8:11]
	s_setprio 0
	s_setprio 1
	v_mfma_f32_16x16x32_bf16 v[52:55], v[170:173], v[186:189], v[52:55]
	v_mfma_f32_16x16x32_bf16 v[48:51], v[178:181], v[186:189], v[48:51]
	v_mfma_f32_16x16x32_bf16 v[36:39], v[170:173], v[194:197], v[36:39]
	v_mfma_f32_16x16x32_bf16 v[32:35], v[178:181], v[194:197], v[32:35]
	v_mfma_f32_16x16x32_bf16 v[20:23], v[170:173], v[202:205], v[20:23]
	v_mfma_f32_16x16x32_bf16 v[16:19], v[178:181], v[202:205], v[16:19]
	v_mfma_f32_16x16x32_bf16 v[4:7], v[170:173], v[216:219], v[4:7]
	v_mfma_f32_16x16x32_bf16 v[0:3], v[178:181], v[216:219], v[0:3]
	s_add_i32 s65, s65, 2
	s_add_u32 s36, s36, 0x100
	s_addc_u32 s37, s37, 0
	s_add_u32 s63, s63, 0x100
	s_addc_u32 s64, s64, 0
	s_cmp_gt_u32 s65, 13
	v_mfma_f32_16x16x32_bf16 v[52:55], v[174:177], v[190:193], v[52:55]
	v_mfma_f32_16x16x32_bf16 v[48:51], v[182:185], v[190:193], v[48:51]
	v_mfma_f32_16x16x32_bf16 v[36:39], v[174:177], v[198:201], v[36:39]
	v_mfma_f32_16x16x32_bf16 v[32:35], v[182:185], v[198:201], v[32:35]
	v_mfma_f32_16x16x32_bf16 v[20:23], v[174:177], v[212:215], v[20:23]
	v_mfma_f32_16x16x32_bf16 v[16:19], v[182:185], v[212:215], v[16:19]
	v_mfma_f32_16x16x32_bf16 v[4:7], v[174:177], v[220:223], v[4:7]
	v_mfma_f32_16x16x32_bf16 v[0:3], v[182:185], v[220:223], v[0:3]
	s_setprio 0
	s_barrier
	s_cbranch_scc0 .LBB0_902
	s_and_b64 vcc, exec, s[14:15]
	s_cbranch_vccz .LBB0_905
	s_barrier

.LBB0_1227:
	ds_read_b128 v[144:147], v151
	ds_read_b128 v[154:157], v151 offset:1024
	ds_read_b128 v[158:161], v151 offset:2048
	ds_read_b128 v[162:165], v151 offset:3072
	ds_read_b128 v[166:169], v152
	ds_read_b128 v[170:173], v152 offset:1024
	ds_read_b128 v[174:177], v152 offset:2048
	ds_read_b128 v[178:181], v152 offset:3072
	s_add_u32 s44, s42, 0xfffc0080
	s_addc_u32 s45, s43, -1
	s_cmp_eq_u32 s67, 12
	s_cselect_b32 s47, s23, s45
	s_cselect_b32 s46, s39, s44
	s_cselect_b32 s45, s21, s66
	s_cselect_b32 s44, s64, s65
	v_lshl_add_u64 v[206:207], s[42:43], 0, v[136:137]
	s_add_i32 m0, s41, 0xc000
	ds_read_b128 v[182:185], v153
	ds_read_b128 v[186:189], v153 offset:1024
	ds_read_b128 v[190:193], v153 offset:2048
	ds_read_b128 v[194:197], v153 offset:3072
	ds_read_b128 v[198:201], v153 offset:4096
	ds_read_b128 v[202:205], v153 offset:5120
	ds_read_b128 v[210:213], v153 offset:6144
	ds_read_b128 v[214:217], v153 offset:7168
	global_load_lds_dwordx4 v[206:207], off
	v_lshl_add_u64 v[206:207], s[42:43], 0, v[138:139]
	s_add_i32 m0, s41, 0xe000
	s_nop 0
	global_load_lds_dwordx4 v[206:207], off
	s_waitcnt vmcnt(8)
	s_waitcnt lgkmcnt(0)
	s_setprio 1
	s_barrier
	v_mfma_f32_16x16x32_bf16 v[120:123], v[144:147], v[182:185], v[120:123]
	v_mfma_f32_16x16x32_bf16 v[112:115], v[158:161], v[182:185], v[112:115]
	v_mfma_f32_16x16x32_bf16 v[104:107], v[144:147], v[190:193], v[104:107]
	v_mfma_f32_16x16x32_bf16 v[96:99], v[158:161], v[190:193], v[96:99]
	v_mfma_f32_16x16x32_bf16 v[88:91], v[144:147], v[198:201], v[88:91]
	v_mfma_f32_16x16x32_bf16 v[80:83], v[158:161], v[198:201], v[80:83]
	v_mfma_f32_16x16x32_bf16 v[72:75], v[144:147], v[210:213], v[72:75]
	v_mfma_f32_16x16x32_bf16 v[64:67], v[158:161], v[210:213], v[64:67]
	v_mfma_f32_16x16x32_bf16 v[120:123], v[154:157], v[186:189], v[120:123]
	v_mfma_f32_16x16x32_bf16 v[112:115], v[162:165], v[186:189], v[112:115]
	v_mfma_f32_16x16x32_bf16 v[104:107], v[154:157], v[194:197], v[104:107]
	v_mfma_f32_16x16x32_bf16 v[96:99], v[162:165], v[194:197], v[96:99]
	v_mfma_f32_16x16x32_bf16 v[88:91], v[154:157], v[202:205], v[88:91]
	v_mfma_f32_16x16x32_bf16 v[80:83], v[162:165], v[202:205], v[80:83]
	v_mfma_f32_16x16x32_bf16 v[72:75], v[154:157], v[214:217], v[72:75]
	v_mfma_f32_16x16x32_bf16 v[64:67], v[162:165], v[214:217], v[64:67]
	s_setprio 0
	s_setprio 1
	v_mfma_f32_16x16x32_bf16 v[124:127], v[166:169], v[182:185], v[124:127]
	v_mfma_f32_16x16x32_bf16 v[116:119], v[174:177], v[182:185], v[116:119]
	v_mfma_f32_16x16x32_bf16 v[108:111], v[166:169], v[190:193], v[108:111]
	v_mfma_f32_16x16x32_bf16 v[100:103], v[174:177], v[190:193], v[100:103]
	v_mfma_f32_16x16x32_bf16 v[92:95], v[166:169], v[198:201], v[92:95]
	v_mfma_f32_16x16x32_bf16 v[84:87], v[174:177], v[198:201], v[84:87]
	v_mfma_f32_16x16x32_bf16 v[76:79], v[166:169], v[210:213], v[76:79]
	v_mfma_f32_16x16x32_bf16 v[68:71], v[174:177], v[210:213], v[68:71]
	v_mfma_f32_16x16x32_bf16 v[124:127], v[170:173], v[186:189], v[124:127]
	v_mfma_f32_16x16x32_bf16 v[116:119], v[178:181], v[186:189], v[116:119]
	v_mfma_f32_16x16x32_bf16 v[108:111], v[170:173], v[194:197], v[108:111]
	v_mfma_f32_16x16x32_bf16 v[100:103], v[178:181], v[194:197], v[100:103]
	v_mfma_f32_16x16x32_bf16 v[92:95], v[170:173], v[202:205], v[92:95]
	v_mfma_f32_16x16x32_bf16 v[84:87], v[178:181], v[202:205], v[84:87]
	v_mfma_f32_16x16x32_bf16 v[76:79], v[170:173], v[214:217], v[76:79]
	v_mfma_f32_16x16x32_bf16 v[68:71], v[178:181], v[214:217], v[68:71]
	s_setprio 0
	s_barrier
	s_add_i32 s68, s62, s52
	v_lshl_add_u64 v[206:207], s[44:45], 0, v[130:131]
	s_mov_b32 m0, s68
	ds_read_b128 v[182:185], v153 offset:16384
	ds_read_b128 v[186:189], v153 offset:17408
	ds_read_b128 v[190:193], v153 offset:18432
	ds_read_b128 v[194:197], v153 offset:19456
	ds_read_b128 v[198:201], v153 offset:20480
	ds_read_b128 v[202:205], v153 offset:21504
	ds_read_b128 v[210:213], v153 offset:22528
	ds_read_b128 v[214:217], v153 offset:23552
	global_load_lds_dwordx4 v[206:207], off
	s_add_i32 m0, s68, 0x2000
	s_add_u32 s68, s44, 0x40000
	v_lshl_add_u64 v[218:219], s[44:45], 0, v[134:135]
	s_addc_u32 s69, s45, 0
	s_add_i32 s70, s63, s52
	global_load_lds_dwordx4 v[218:219], off
	v_lshl_add_u64 v[220:221], s[68:69], 0, v[130:131]
	s_mov_b32 m0, s70
	v_lshl_add_u64 v[222:223], s[46:47], 0, v[132:133]
	global_load_lds_dwordx4 v[220:221], off
	v_lshl_add_u64 v[220:221], s[68:69], 0, v[134:135]
	s_add_i32 m0, s70, 0x2000
	s_nop 0
	global_load_lds_dwordx4 v[220:221], off
	v_lshl_add_u64 v[220:221], s[46:47], 0, v[128:129]
	s_mov_b32 m0, s41
	s_nop 0
	global_load_lds_dwordx4 v[220:221], off
	s_mov_b32 m0, s53
	s_nop 0
	global_load_lds_dwordx4 v[222:223], off
	s_waitcnt vmcnt(8)
	s_waitcnt lgkmcnt(0)
	s_setprio 1
	s_barrier
	v_mfma_f32_16x16x32_bf16 v[56:59], v[144:147], v[182:185], v[56:59]
	v_mfma_f32_16x16x32_bf16 v[48:51], v[158:161], v[182:185], v[48:51]
	v_mfma_f32_16x16x32_bf16 v[40:43], v[144:147], v[190:193], v[40:43]
	v_mfma_f32_16x16x32_bf16 v[32:35], v[158:161], v[190:193], v[32:35]
	v_mfma_f32_16x16x32_bf16 v[24:27], v[144:147], v[198:201], v[24:27]
	v_mfma_f32_16x16x32_bf16 v[16:19], v[158:161], v[198:201], v[16:19]
	v_mfma_f32_16x16x32_bf16 v[8:11], v[144:147], v[210:213], v[8:11]
	v_mfma_f32_16x16x32_bf16 v[0:3], v[158:161], v[210:213], v[0:3]
	v_mfma_f32_16x16x32_bf16 v[56:59], v[154:157], v[186:189], v[56:59]
	v_mfma_f32_16x16x32_bf16 v[48:51], v[162:165], v[186:189], v[48:51]
	v_mfma_f32_16x16x32_bf16 v[40:43], v[154:157], v[194:197], v[40:43]
	v_mfma_f32_16x16x32_bf16 v[32:35], v[162:165], v[194:197], v[32:35]
	v_mfma_f32_16x16x32_bf16 v[24:27], v[154:157], v[202:205], v[24:27]
	v_mfma_f32_16x16x32_bf16 v[16:19], v[162:165], v[202:205], v[16:19]
	v_mfma_f32_16x16x32_bf16 v[8:11], v[154:157], v[214:217], v[8:11]
	v_mfma_f32_16x16x32_bf16 v[0:3], v[162:165], v[214:217], v[0:3]
	s_setprio 0
	s_setprio 1
	v_mfma_f32_16x16x32_bf16 v[60:63], v[166:169], v[182:185], v[60:63]
	v_mfma_f32_16x16x32_bf16 v[52:55], v[174:177], v[182:185], v[52:55]
	v_mfma_f32_16x16x32_bf16 v[44:47], v[166:169], v[190:193], v[44:47]
	v_mfma_f32_16x16x32_bf16 v[36:39], v[174:177], v[190:193], v[36:39]
	v_mfma_f32_16x16x32_bf16 v[28:31], v[166:169], v[198:201], v[28:31]
	v_mfma_f32_16x16x32_bf16 v[20:23], v[174:177], v[198:201], v[20:23]
	v_mfma_f32_16x16x32_bf16 v[12:15], v[166:169], v[210:213], v[12:15]
	v_mfma_f32_16x16x32_bf16 v[4:7], v[174:177], v[210:213], v[4:7]
	v_mfma_f32_16x16x32_bf16 v[60:63], v[170:173], v[186:189], v[60:63]
	v_mfma_f32_16x16x32_bf16 v[52:55], v[178:181], v[186:189], v[52:55]
	v_mfma_f32_16x16x32_bf16 v[44:47], v[170:173], v[194:197], v[44:47]
	v_mfma_f32_16x16x32_bf16 v[36:39], v[178:181], v[194:197], v[36:39]
	v_mfma_f32_16x16x32_bf16 v[28:31], v[170:173], v[202:205], v[28:31]
	v_mfma_f32_16x16x32_bf16 v[20:23], v[178:181], v[202:205], v[20:23]
	v_mfma_f32_16x16x32_bf16 v[12:15], v[170:173], v[214:217], v[12:15]
	v_mfma_f32_16x16x32_bf16 v[4:7], v[178:181], v[214:217], v[4:7]
	s_setprio 0
	s_barrier
	s_add_i32 s68, 0, 0x18000
	s_add_i32 s69, 0, 0x1c000
	v_add_u32_e32 v162, s68, v149
	v_add_u32_e32 v178, s69, v149
	ds_read_b128 v[144:147], v162
	ds_read_b128 v[154:157], v162 offset:1024
	ds_read_b128 v[158:161], v162 offset:2048
	ds_read_b128 v[162:165], v162 offset:3072
	ds_read_b128 v[166:169], v178
	ds_read_b128 v[170:173], v178 offset:1024
	ds_read_b128 v[174:177], v178 offset:2048
	ds_read_b128 v[178:181], v178 offset:3072
	s_add_u32 s46, s46, 0x40000
	s_addc_u32 s47, s47, 0
	s_mov_b32 m0, s54
	v_lshl_add_u64 v[224:225], s[46:47], 0, v[128:129]
	ds_read_b128 v[182:185], v153 offset:32768
	ds_read_b128 v[186:189], v153 offset:33792
	ds_read_b128 v[190:193], v153 offset:34816
	ds_read_b128 v[194:197], v153 offset:35840
	ds_read_b128 v[198:201], v153 offset:36864
	ds_read_b128 v[202:205], v153 offset:37888
	ds_read_b128 v[210:213], v153 offset:38912
	ds_read_b128 v[214:217], v153 offset:39936
	global_load_lds_dwordx4 v[224:225], off
	v_lshl_add_u64 v[224:225], s[46:47], 0, v[132:133]
	s_mov_b32 m0, s55
	s_nop 0
	global_load_lds_dwordx4 v[224:225], off
	s_waitcnt vmcnt(8)
	s_waitcnt lgkmcnt(0)
	s_setprio 1
	s_barrier
	v_mfma_f32_16x16x32_bf16 v[120:123], v[144:147], v[182:185], v[120:123]
	v_mfma_f32_16x16x32_bf16 v[112:115], v[158:161], v[182:185], v[112:115]
	v_mfma_f32_16x16x32_bf16 v[104:107], v[144:147], v[190:193], v[104:107]
	v_mfma_f32_16x16x32_bf16 v[96:99], v[158:161], v[190:193], v[96:99]
	v_mfma_f32_16x16x32_bf16 v[88:91], v[144:147], v[198:201], v[88:91]
	v_mfma_f32_16x16x32_bf16 v[80:83], v[158:161], v[198:201], v[80:83]
	v_mfma_f32_16x16x32_bf16 v[72:75], v[144:147], v[210:213], v[72:75]
	v_mfma_f32_16x16x32_bf16 v[64:67], v[158:161], v[210:213], v[64:67]
	v_mfma_f32_16x16x32_bf16 v[120:123], v[154:157], v[186:189], v[120:123]
	v_mfma_f32_16x16x32_bf16 v[112:115], v[162:165], v[186:189], v[112:115]
	v_mfma_f32_16x16x32_bf16 v[104:107], v[154:157], v[194:197], v[104:107]
	v_mfma_f32_16x16x32_bf16 v[96:99], v[162:165], v[194:197], v[96:99]
	v_mfma_f32_16x16x32_bf16 v[88:91], v[154:157], v[202:205], v[88:91]
	v_mfma_f32_16x16x32_bf16 v[80:83], v[162:165], v[202:205], v[80:83]
	v_mfma_f32_16x16x32_bf16 v[72:75], v[154:157], v[214:217], v[72:75]
	v_mfma_f32_16x16x32_bf16 v[64:67], v[162:165], v[214:217], v[64:67]
	s_setprio 0
	s_setprio 1
	v_mfma_f32_16x16x32_bf16 v[124:127], v[166:169], v[182:185], v[124:127]
	v_mfma_f32_16x16x32_bf16 v[116:119], v[174:177], v[182:185], v[116:119]
	v_mfma_f32_16x16x32_bf16 v[108:111], v[166:169], v[190:193], v[108:111]
	v_mfma_f32_16x16x32_bf16 v[100:103], v[174:177], v[190:193], v[100:103]
	v_mfma_f32_16x16x32_bf16 v[92:95], v[166:169], v[198:201], v[92:95]
	v_mfma_f32_16x16x32_bf16 v[84:87], v[174:177], v[198:201], v[84:87]
	v_mfma_f32_16x16x32_bf16 v[76:79], v[166:169], v[210:213], v[76:79]
	v_mfma_f32_16x16x32_bf16 v[68:71], v[174:177], v[210:213], v[68:71]
	v_mfma_f32_16x16x32_bf16 v[124:127], v[170:173], v[186:189], v[124:127]
	v_mfma_f32_16x16x32_bf16 v[116:119], v[178:181], v[186:189], v[116:119]
	v_mfma_f32_16x16x32_bf16 v[108:111], v[170:173], v[194:197], v[108:111]
	v_mfma_f32_16x16x32_bf16 v[100:103], v[178:181], v[194:197], v[100:103]
	v_mfma_f32_16x16x32_bf16 v[92:95], v[170:173], v[202:205], v[92:95]
	v_mfma_f32_16x16x32_bf16 v[84:87], v[178:181], v[202:205], v[84:87]
	v_mfma_f32_16x16x32_bf16 v[76:79], v[170:173], v[214:217], v[76:79]
	v_mfma_f32_16x16x32_bf16 v[68:71], v[178:181], v[214:217], v[68:71]
	s_setprio 0
	s_barrier
	s_add_i32 s46, s68, s52
	v_lshl_add_u64 v[206:207], v[206:207], 0, s[16:17]
	s_mov_b32 m0, s46
	ds_read_b128 v[182:185], v153 offset:49152
	ds_read_b128 v[186:189], v153 offset:50176
	ds_read_b128 v[190:193], v153 offset:51200
	ds_read_b128 v[194:197], v153 offset:52224
	ds_read_b128 v[198:201], v153 offset:53248
	ds_read_b128 v[202:205], v153 offset:54272
	ds_read_b128 v[210:213], v153 offset:55296
	ds_read_b128 v[214:217], v153 offset:56320
	global_load_lds_dwordx4 v[206:207], off
	s_add_i32 m0, s46, 0x2000
	s_add_u32 s44, s44, 0x40080
	v_lshl_add_u64 v[206:207], v[218:219], 0, s[16:17]
	s_addc_u32 s45, s45, 0
	s_add_i32 s46, s69, s52
	global_load_lds_dwordx4 v[206:207], off
	v_lshl_add_u64 v[206:207], s[44:45], 0, v[130:131]
	s_mov_b32 m0, s46
	s_nop 0
	global_load_lds_dwordx4 v[206:207], off
	v_lshl_add_u64 v[206:207], s[44:45], 0, v[134:135]
	s_add_i32 m0, s46, 0x2000
	s_nop 0
	global_load_lds_dwordx4 v[206:207], off
	v_lshl_add_u64 v[206:207], v[220:221], 0, s[16:17]
	s_mov_b32 m0, s57
	s_nop 0
	global_load_lds_dwordx4 v[206:207], off
	v_lshl_add_u64 v[206:207], v[222:223], 0, s[16:17]
	s_mov_b32 m0, s58
	s_nop 0
	global_load_lds_dwordx4 v[206:207], off
	s_waitcnt vmcnt(8)
	s_waitcnt lgkmcnt(0)
	s_setprio 1
	s_barrier
	v_mfma_f32_16x16x32_bf16 v[56:59], v[144:147], v[182:185], v[56:59]
	v_mfma_f32_16x16x32_bf16 v[48:51], v[158:161], v[182:185], v[48:51]
	v_mfma_f32_16x16x32_bf16 v[40:43], v[144:147], v[190:193], v[40:43]
	v_mfma_f32_16x16x32_bf16 v[32:35], v[158:161], v[190:193], v[32:35]
	v_mfma_f32_16x16x32_bf16 v[24:27], v[144:147], v[198:201], v[24:27]
	v_mfma_f32_16x16x32_bf16 v[16:19], v[158:161], v[198:201], v[16:19]
	v_mfma_f32_16x16x32_bf16 v[8:11], v[144:147], v[210:213], v[8:11]
	v_mfma_f32_16x16x32_bf16 v[0:3], v[158:161], v[210:213], v[0:3]
	v_mfma_f32_16x16x32_bf16 v[56:59], v[154:157], v[186:189], v[56:59]
	v_mfma_f32_16x16x32_bf16 v[48:51], v[162:165], v[186:189], v[48:51]
	v_mfma_f32_16x16x32_bf16 v[40:43], v[154:157], v[194:197], v[40:43]
	v_mfma_f32_16x16x32_bf16 v[32:35], v[162:165], v[194:197], v[32:35]
	v_mfma_f32_16x16x32_bf16 v[24:27], v[154:157], v[202:205], v[24:27]
	v_mfma_f32_16x16x32_bf16 v[16:19], v[162:165], v[202:205], v[16:19]
	v_mfma_f32_16x16x32_bf16 v[8:11], v[154:157], v[214:217], v[8:11]
	v_mfma_f32_16x16x32_bf16 v[0:3], v[162:165], v[214:217], v[0:3]
	s_setprio 0
	s_setprio 1
	v_mfma_f32_16x16x32_bf16 v[60:63], v[166:169], v[182:185], v[60:63]
	v_mfma_f32_16x16x32_bf16 v[52:55], v[174:177], v[182:185], v[52:55]
	v_mfma_f32_16x16x32_bf16 v[44:47], v[166:169], v[190:193], v[44:47]
	v_mfma_f32_16x16x32_bf16 v[36:39], v[174:177], v[190:193], v[36:39]
	v_mfma_f32_16x16x32_bf16 v[28:31], v[166:169], v[198:201], v[28:31]
	v_mfma_f32_16x16x32_bf16 v[20:23], v[174:177], v[198:201], v[20:23]
	v_mfma_f32_16x16x32_bf16 v[12:15], v[166:169], v[210:213], v[12:15]
	v_mfma_f32_16x16x32_bf16 v[4:7], v[174:177], v[210:213], v[4:7]
	s_add_i32 s67, s67, 2
	s_add_u32 s42, s42, 0x100
	s_addc_u32 s43, s43, 0
	s_add_u32 s65, s65, 0x100
	s_addc_u32 s66, s66, 0
	s_cmp_gt_u32 s67, 13
	v_mfma_f32_16x16x32_bf16 v[60:63], v[170:173], v[186:189], v[60:63]
	v_mfma_f32_16x16x32_bf16 v[52:55], v[178:181], v[186:189], v[52:55]
	v_mfma_f32_16x16x32_bf16 v[44:47], v[170:173], v[194:197], v[44:47]
	v_mfma_f32_16x16x32_bf16 v[36:39], v[178:181], v[194:197], v[36:39]
	v_mfma_f32_16x16x32_bf16 v[28:31], v[170:173], v[202:205], v[28:31]
	v_mfma_f32_16x16x32_bf16 v[20:23], v[178:181], v[202:205], v[20:23]
	v_mfma_f32_16x16x32_bf16 v[12:15], v[170:173], v[214:217], v[12:15]
	v_mfma_f32_16x16x32_bf16 v[4:7], v[178:181], v[214:217], v[4:7]
	s_setprio 0
	s_barrier
	s_cbranch_scc0 .LBB0_1227
	s_and_b64 vcc, exec, s[18:19]
	s_cbranch_vccz .LBB0_1230
	s_barrier

.LBB0_1322:
	ds_read_b128 v[152:155], v149
	ds_read_b128 v[156:159], v149 offset:1024
	ds_read_b128 v[160:163], v149 offset:2048
	ds_read_b128 v[164:167], v149 offset:3072
	ds_read_b128 v[168:171], v150
	ds_read_b128 v[172:175], v150 offset:1024
	ds_read_b128 v[176:179], v150 offset:2048
	ds_read_b128 v[180:183], v150 offset:3072
	s_add_u32 s46, s44, 0xfffc0080
	s_addc_u32 s47, s45, -1
	s_cmp_eq_u32 s75, 12
	s_cselect_b32 s49, s37, s47
	s_cselect_b32 s48, s71, s46
	s_cselect_b32 s47, s25, s74
	s_cselect_b32 s46, s72, s73
	v_lshl_add_u64 v[144:145], s[44:45], 0, v[136:137]
	s_add_i32 m0, s43, 0xc000
	ds_read_b128 v[184:187], v151
	ds_read_b128 v[188:191], v151 offset:1024
	ds_read_b128 v[192:195], v151 offset:2048
	ds_read_b128 v[196:199], v151 offset:3072
	ds_read_b128 v[200:203], v151 offset:4096
	ds_read_b128 v[204:207], v151 offset:5120
	ds_read_b128 v[210:213], v151 offset:6144
	ds_read_b128 v[214:217], v151 offset:7168
	global_load_lds_dwordx4 v[144:145], off
	v_lshl_add_u64 v[144:145], s[44:45], 0, v[138:139]
	s_add_i32 m0, s43, 0xe000
	s_nop 0
	global_load_lds_dwordx4 v[144:145], off
	s_waitcnt vmcnt(8)
	s_waitcnt lgkmcnt(0)
	s_setprio 1
	s_barrier
	v_mfma_f32_16x16x32_bf16 v[124:127], v[152:155], v[184:187], v[124:127]
	v_mfma_f32_16x16x32_bf16 v[120:123], v[160:163], v[184:187], v[120:123]
	v_mfma_f32_16x16x32_bf16 v[108:111], v[152:155], v[192:195], v[108:111]
	v_mfma_f32_16x16x32_bf16 v[104:107], v[160:163], v[192:195], v[104:107]
	v_mfma_f32_16x16x32_bf16 v[92:95], v[152:155], v[200:203], v[92:95]
	v_mfma_f32_16x16x32_bf16 v[88:91], v[160:163], v[200:203], v[88:91]
	v_mfma_f32_16x16x32_bf16 v[76:79], v[152:155], v[210:213], v[76:79]
	v_mfma_f32_16x16x32_bf16 v[72:75], v[160:163], v[210:213], v[72:75]
	v_mfma_f32_16x16x32_bf16 v[124:127], v[156:159], v[188:191], v[124:127]
	v_mfma_f32_16x16x32_bf16 v[120:123], v[164:167], v[188:191], v[120:123]
	v_mfma_f32_16x16x32_bf16 v[108:111], v[156:159], v[196:199], v[108:111]
	v_mfma_f32_16x16x32_bf16 v[104:107], v[164:167], v[196:199], v[104:107]
	v_mfma_f32_16x16x32_bf16 v[92:95], v[156:159], v[204:207], v[92:95]
	v_mfma_f32_16x16x32_bf16 v[88:91], v[164:167], v[204:207], v[88:91]
	v_mfma_f32_16x16x32_bf16 v[76:79], v[156:159], v[214:217], v[76:79]
	v_mfma_f32_16x16x32_bf16 v[72:75], v[164:167], v[214:217], v[72:75]
	s_setprio 0
	s_setprio 1
	v_mfma_f32_16x16x32_bf16 v[116:119], v[168:171], v[184:187], v[116:119]
	v_mfma_f32_16x16x32_bf16 v[112:115], v[176:179], v[184:187], v[112:115]
	v_mfma_f32_16x16x32_bf16 v[100:103], v[168:171], v[192:195], v[100:103]
	v_mfma_f32_16x16x32_bf16 v[96:99], v[176:179], v[192:195], v[96:99]
	v_mfma_f32_16x16x32_bf16 v[84:87], v[168:171], v[200:203], v[84:87]
	v_mfma_f32_16x16x32_bf16 v[80:83], v[176:179], v[200:203], v[80:83]
	v_mfma_f32_16x16x32_bf16 v[68:71], v[168:171], v[210:213], v[68:71]
	v_mfma_f32_16x16x32_bf16 v[64:67], v[176:179], v[210:213], v[64:67]
	v_mfma_f32_16x16x32_bf16 v[116:119], v[172:175], v[188:191], v[116:119]
	v_mfma_f32_16x16x32_bf16 v[112:115], v[180:183], v[188:191], v[112:115]
	v_mfma_f32_16x16x32_bf16 v[100:103], v[172:175], v[196:199], v[100:103]
	v_mfma_f32_16x16x32_bf16 v[96:99], v[180:183], v[196:199], v[96:99]
	v_mfma_f32_16x16x32_bf16 v[84:87], v[172:175], v[204:207], v[84:87]
	v_mfma_f32_16x16x32_bf16 v[80:83], v[180:183], v[204:207], v[80:83]
	v_mfma_f32_16x16x32_bf16 v[68:71], v[172:175], v[214:217], v[68:71]
	v_mfma_f32_16x16x32_bf16 v[64:67], v[180:183], v[214:217], v[64:67]
	s_setprio 0
	s_barrier
	s_add_i32 s76, s64, s55
	v_lshl_add_u64 v[144:145], s[46:47], 0, v[130:131]
	s_mov_b32 m0, s76
	ds_read_b128 v[184:187], v151 offset:16384
	ds_read_b128 v[188:191], v151 offset:17408
	ds_read_b128 v[192:195], v151 offset:18432
	ds_read_b128 v[196:199], v151 offset:19456
	ds_read_b128 v[200:203], v151 offset:20480
	ds_read_b128 v[204:207], v151 offset:21504
	ds_read_b128 v[210:213], v151 offset:22528
	ds_read_b128 v[214:217], v151 offset:23552
	global_load_lds_dwordx4 v[144:145], off
	s_add_i32 m0, s76, 0x2000
	s_add_u32 s76, s46, 0x40000
	v_lshl_add_u64 v[218:219], s[46:47], 0, v[134:135]
	s_addc_u32 s77, s47, 0
	s_add_i32 s78, s65, s55
	global_load_lds_dwordx4 v[218:219], off
	v_lshl_add_u64 v[220:221], s[76:77], 0, v[130:131]
	s_mov_b32 m0, s78
	v_lshl_add_u64 v[222:223], s[48:49], 0, v[132:133]
	global_load_lds_dwordx4 v[220:221], off
	v_lshl_add_u64 v[220:221], s[76:77], 0, v[134:135]
	s_add_i32 m0, s78, 0x2000
	s_nop 0
	global_load_lds_dwordx4 v[220:221], off
	v_lshl_add_u64 v[220:221], s[48:49], 0, v[128:129]
	s_mov_b32 m0, s43
	s_nop 0
	global_load_lds_dwordx4 v[220:221], off
	s_mov_b32 m0, s56
	s_nop 0
	global_load_lds_dwordx4 v[222:223], off
	s_waitcnt vmcnt(8)
	s_waitcnt lgkmcnt(0)
	s_setprio 1
	s_barrier
	v_mfma_f32_16x16x32_bf16 v[60:63], v[152:155], v[184:187], v[60:63]
	v_mfma_f32_16x16x32_bf16 v[56:59], v[160:163], v[184:187], v[56:59]
	v_mfma_f32_16x16x32_bf16 v[44:47], v[152:155], v[192:195], v[44:47]
	v_mfma_f32_16x16x32_bf16 v[40:43], v[160:163], v[192:195], v[40:43]
	v_mfma_f32_16x16x32_bf16 v[28:31], v[152:155], v[200:203], v[28:31]
	v_mfma_f32_16x16x32_bf16 v[24:27], v[160:163], v[200:203], v[24:27]
	v_mfma_f32_16x16x32_bf16 v[12:15], v[152:155], v[210:213], v[12:15]
	v_mfma_f32_16x16x32_bf16 v[8:11], v[160:163], v[210:213], v[8:11]
	v_mfma_f32_16x16x32_bf16 v[60:63], v[156:159], v[188:191], v[60:63]
	v_mfma_f32_16x16x32_bf16 v[56:59], v[164:167], v[188:191], v[56:59]
	v_mfma_f32_16x16x32_bf16 v[44:47], v[156:159], v[196:199], v[44:47]
	v_mfma_f32_16x16x32_bf16 v[40:43], v[164:167], v[196:199], v[40:43]
	v_mfma_f32_16x16x32_bf16 v[28:31], v[156:159], v[204:207], v[28:31]
	v_mfma_f32_16x16x32_bf16 v[24:27], v[164:167], v[204:207], v[24:27]
	v_mfma_f32_16x16x32_bf16 v[12:15], v[156:159], v[214:217], v[12:15]
	v_mfma_f32_16x16x32_bf16 v[8:11], v[164:167], v[214:217], v[8:11]
	s_setprio 0
	s_setprio 1
	v_mfma_f32_16x16x32_bf16 v[52:55], v[168:171], v[184:187], v[52:55]
	v_mfma_f32_16x16x32_bf16 v[48:51], v[176:179], v[184:187], v[48:51]
	v_mfma_f32_16x16x32_bf16 v[36:39], v[168:171], v[192:195], v[36:39]
	v_mfma_f32_16x16x32_bf16 v[32:35], v[176:179], v[192:195], v[32:35]
	v_mfma_f32_16x16x32_bf16 v[20:23], v[168:171], v[200:203], v[20:23]
	v_mfma_f32_16x16x32_bf16 v[16:19], v[176:179], v[200:203], v[16:19]
	v_mfma_f32_16x16x32_bf16 v[4:7], v[168:171], v[210:213], v[4:7]
	v_mfma_f32_16x16x32_bf16 v[0:3], v[176:179], v[210:213], v[0:3]
	v_mfma_f32_16x16x32_bf16 v[52:55], v[172:175], v[188:191], v[52:55]
	v_mfma_f32_16x16x32_bf16 v[48:51], v[180:183], v[188:191], v[48:51]
	v_mfma_f32_16x16x32_bf16 v[36:39], v[172:175], v[196:199], v[36:39]
	v_mfma_f32_16x16x32_bf16 v[32:35], v[180:183], v[196:199], v[32:35]
	v_mfma_f32_16x16x32_bf16 v[20:23], v[172:175], v[204:207], v[20:23]
	v_mfma_f32_16x16x32_bf16 v[16:19], v[180:183], v[204:207], v[16:19]
	v_mfma_f32_16x16x32_bf16 v[4:7], v[172:175], v[214:217], v[4:7]
	v_mfma_f32_16x16x32_bf16 v[0:3], v[180:183], v[214:217], v[0:3]
	s_setprio 0
	s_barrier
	s_add_i32 s76, 0, 0x18000
	s_add_i32 s77, 0, 0x1c000
	v_add_u32_e32 v164, s76, v147
	v_add_u32_e32 v180, s77, v147
	ds_read_b128 v[152:155], v164
	ds_read_b128 v[156:159], v164 offset:1024
	ds_read_b128 v[160:163], v164 offset:2048
	ds_read_b128 v[164:167], v164 offset:3072
	ds_read_b128 v[168:171], v180
	ds_read_b128 v[172:175], v180 offset:1024
	ds_read_b128 v[176:179], v180 offset:2048
	ds_read_b128 v[180:183], v180 offset:3072
	s_add_u32 s48, s48, 0x40000
	s_addc_u32 s49, s49, 0
	s_mov_b32 m0, s57
	v_lshl_add_u64 v[224:225], s[48:49], 0, v[128:129]
	ds_read_b128 v[184:187], v151 offset:32768
	ds_read_b128 v[188:191], v151 offset:33792
	ds_read_b128 v[192:195], v151 offset:34816
	ds_read_b128 v[196:199], v151 offset:35840
	ds_read_b128 v[200:203], v151 offset:36864
	ds_read_b128 v[204:207], v151 offset:37888
	ds_read_b128 v[210:213], v151 offset:38912
	ds_read_b128 v[214:217], v151 offset:39936
	global_load_lds_dwordx4 v[224:225], off
	v_lshl_add_u64 v[224:225], s[48:49], 0, v[132:133]
	s_mov_b32 m0, s58
	s_nop 0
	global_load_lds_dwordx4 v[224:225], off
	s_waitcnt vmcnt(8)
	s_waitcnt lgkmcnt(0)
	s_setprio 1
	s_barrier
	v_mfma_f32_16x16x32_bf16 v[124:127], v[152:155], v[184:187], v[124:127]
	v_mfma_f32_16x16x32_bf16 v[120:123], v[160:163], v[184:187], v[120:123]
	v_mfma_f32_16x16x32_bf16 v[108:111], v[152:155], v[192:195], v[108:111]
	v_mfma_f32_16x16x32_bf16 v[104:107], v[160:163], v[192:195], v[104:107]
	v_mfma_f32_16x16x32_bf16 v[92:95], v[152:155], v[200:203], v[92:95]
	v_mfma_f32_16x16x32_bf16 v[88:91], v[160:163], v[200:203], v[88:91]
	v_mfma_f32_16x16x32_bf16 v[76:79], v[152:155], v[210:213], v[76:79]
	v_mfma_f32_16x16x32_bf16 v[72:75], v[160:163], v[210:213], v[72:75]
	v_mfma_f32_16x16x32_bf16 v[124:127], v[156:159], v[188:191], v[124:127]
	v_mfma_f32_16x16x32_bf16 v[120:123], v[164:167], v[188:191], v[120:123]
	v_mfma_f32_16x16x32_bf16 v[108:111], v[156:159], v[196:199], v[108:111]
	v_mfma_f32_16x16x32_bf16 v[104:107], v[164:167], v[196:199], v[104:107]
	v_mfma_f32_16x16x32_bf16 v[92:95], v[156:159], v[204:207], v[92:95]
	v_mfma_f32_16x16x32_bf16 v[88:91], v[164:167], v[204:207], v[88:91]
	v_mfma_f32_16x16x32_bf16 v[76:79], v[156:159], v[214:217], v[76:79]
	v_mfma_f32_16x16x32_bf16 v[72:75], v[164:167], v[214:217], v[72:75]
	s_setprio 0
	s_setprio 1
	v_mfma_f32_16x16x32_bf16 v[116:119], v[168:171], v[184:187], v[116:119]
	v_mfma_f32_16x16x32_bf16 v[112:115], v[176:179], v[184:187], v[112:115]
	v_mfma_f32_16x16x32_bf16 v[100:103], v[168:171], v[192:195], v[100:103]
	v_mfma_f32_16x16x32_bf16 v[96:99], v[176:179], v[192:195], v[96:99]
	v_mfma_f32_16x16x32_bf16 v[84:87], v[168:171], v[200:203], v[84:87]
	v_mfma_f32_16x16x32_bf16 v[80:83], v[176:179], v[200:203], v[80:83]
	v_mfma_f32_16x16x32_bf16 v[68:71], v[168:171], v[210:213], v[68:71]
	v_mfma_f32_16x16x32_bf16 v[64:67], v[176:179], v[210:213], v[64:67]
	v_mfma_f32_16x16x32_bf16 v[116:119], v[172:175], v[188:191], v[116:119]
	v_mfma_f32_16x16x32_bf16 v[112:115], v[180:183], v[188:191], v[112:115]
	v_mfma_f32_16x16x32_bf16 v[100:103], v[172:175], v[196:199], v[100:103]
	v_mfma_f32_16x16x32_bf16 v[96:99], v[180:183], v[196:199], v[96:99]
	v_mfma_f32_16x16x32_bf16 v[84:87], v[172:175], v[204:207], v[84:87]
	v_mfma_f32_16x16x32_bf16 v[80:83], v[180:183], v[204:207], v[80:83]
	v_mfma_f32_16x16x32_bf16 v[68:71], v[172:175], v[214:217], v[68:71]
	v_mfma_f32_16x16x32_bf16 v[64:67], v[180:183], v[214:217], v[64:67]
	s_setprio 0
	s_barrier
	s_add_i32 s48, s76, s55
	v_lshl_add_u64 v[144:145], v[144:145], 0, s[12:13]
	s_mov_b32 m0, s48
	ds_read_b128 v[184:187], v151 offset:49152
	ds_read_b128 v[188:191], v151 offset:50176
	ds_read_b128 v[192:195], v151 offset:51200
	ds_read_b128 v[196:199], v151 offset:52224
	ds_read_b128 v[200:203], v151 offset:53248
	ds_read_b128 v[204:207], v151 offset:54272
	ds_read_b128 v[210:213], v151 offset:55296
	ds_read_b128 v[214:217], v151 offset:56320
	global_load_lds_dwordx4 v[144:145], off
	s_add_i32 m0, s48, 0x2000
	s_add_u32 s46, s46, 0x40080
	v_lshl_add_u64 v[144:145], v[218:219], 0, s[12:13]
	s_addc_u32 s47, s47, 0
	s_add_i32 s48, s77, s55
	global_load_lds_dwordx4 v[144:145], off
	v_lshl_add_u64 v[144:145], s[46:47], 0, v[130:131]
	s_mov_b32 m0, s48
	s_nop 0
	global_load_lds_dwordx4 v[144:145], off
	v_lshl_add_u64 v[144:145], s[46:47], 0, v[134:135]
	s_add_i32 m0, s48, 0x2000
	s_nop 0
	global_load_lds_dwordx4 v[144:145], off
	v_lshl_add_u64 v[144:145], v[220:221], 0, s[12:13]
	s_mov_b32 m0, s60
	s_nop 0
	global_load_lds_dwordx4 v[144:145], off
	v_lshl_add_u64 v[144:145], v[222:223], 0, s[12:13]
	s_mov_b32 m0, s61
	s_nop 0
	global_load_lds_dwordx4 v[144:145], off
	s_waitcnt vmcnt(8)
	s_waitcnt lgkmcnt(0)
	s_setprio 1
	s_barrier
	v_mfma_f32_16x16x32_bf16 v[60:63], v[152:155], v[184:187], v[60:63]
	v_mfma_f32_16x16x32_bf16 v[56:59], v[160:163], v[184:187], v[56:59]
	v_mfma_f32_16x16x32_bf16 v[44:47], v[152:155], v[192:195], v[44:47]
	v_mfma_f32_16x16x32_bf16 v[40:43], v[160:163], v[192:195], v[40:43]
	v_mfma_f32_16x16x32_bf16 v[28:31], v[152:155], v[200:203], v[28:31]
	v_mfma_f32_16x16x32_bf16 v[24:27], v[160:163], v[200:203], v[24:27]
	v_mfma_f32_16x16x32_bf16 v[12:15], v[152:155], v[210:213], v[12:15]
	v_mfma_f32_16x16x32_bf16 v[8:11], v[160:163], v[210:213], v[8:11]
	v_mfma_f32_16x16x32_bf16 v[60:63], v[156:159], v[188:191], v[60:63]
	v_mfma_f32_16x16x32_bf16 v[56:59], v[164:167], v[188:191], v[56:59]
	v_mfma_f32_16x16x32_bf16 v[44:47], v[156:159], v[196:199], v[44:47]
	v_mfma_f32_16x16x32_bf16 v[40:43], v[164:167], v[196:199], v[40:43]
	v_mfma_f32_16x16x32_bf16 v[28:31], v[156:159], v[204:207], v[28:31]
	v_mfma_f32_16x16x32_bf16 v[24:27], v[164:167], v[204:207], v[24:27]
	v_mfma_f32_16x16x32_bf16 v[12:15], v[156:159], v[214:217], v[12:15]
	v_mfma_f32_16x16x32_bf16 v[8:11], v[164:167], v[214:217], v[8:11]
	s_setprio 0
	s_setprio 1
	v_mfma_f32_16x16x32_bf16 v[52:55], v[168:171], v[184:187], v[52:55]
	v_mfma_f32_16x16x32_bf16 v[48:51], v[176:179], v[184:187], v[48:51]
	v_mfma_f32_16x16x32_bf16 v[36:39], v[168:171], v[192:195], v[36:39]
	v_mfma_f32_16x16x32_bf16 v[32:35], v[176:179], v[192:195], v[32:35]
	v_mfma_f32_16x16x32_bf16 v[20:23], v[168:171], v[200:203], v[20:23]
	v_mfma_f32_16x16x32_bf16 v[16:19], v[176:179], v[200:203], v[16:19]
	v_mfma_f32_16x16x32_bf16 v[4:7], v[168:171], v[210:213], v[4:7]
	v_mfma_f32_16x16x32_bf16 v[0:3], v[176:179], v[210:213], v[0:3]
	s_add_i32 s75, s75, 2
	s_add_u32 s44, s44, 0x100
	s_addc_u32 s45, s45, 0
	s_add_u32 s73, s73, 0x100
	s_addc_u32 s74, s74, 0
	s_cmp_gt_u32 s75, 13
	v_mfma_f32_16x16x32_bf16 v[52:55], v[172:175], v[188:191], v[52:55]
	v_mfma_f32_16x16x32_bf16 v[48:51], v[180:183], v[188:191], v[48:51]
	v_mfma_f32_16x16x32_bf16 v[36:39], v[172:175], v[196:199], v[36:39]
	v_mfma_f32_16x16x32_bf16 v[32:35], v[180:183], v[196:199], v[32:35]
	v_mfma_f32_16x16x32_bf16 v[20:23], v[172:175], v[204:207], v[20:23]
	v_mfma_f32_16x16x32_bf16 v[16:19], v[180:183], v[204:207], v[16:19]
	v_mfma_f32_16x16x32_bf16 v[4:7], v[172:175], v[214:217], v[4:7]
	v_mfma_f32_16x16x32_bf16 v[0:3], v[180:183], v[214:217], v[0:3]
	s_setprio 0
	s_barrier
	s_cbranch_scc0 .LBB0_1322
	s_and_b64 vcc, exec, s[14:15]
	s_cbranch_vccz .LBB0_1325
	s_barrier

.LBB0_1402:
	ds_read_b128 v[144:147], v155
	ds_read_b128 v[148:151], v155 offset:1024
	ds_read_b128 v[160:163], v155 offset:2048
	ds_read_b128 v[164:167], v155 offset:3072
	ds_read_b128 v[168:171], v156
	ds_read_b128 v[172:175], v156 offset:1024
	ds_read_b128 v[176:179], v156 offset:2048
	ds_read_b128 v[180:183], v156 offset:3072
	s_add_u32 s42, s40, 0xfff00080
	s_addc_u32 s43, s41, -1
	s_cmp_eq_u32 s63, 60
	s_cselect_b32 s45, s31, s43
	s_cselect_b32 s44, s59, s42
	s_cselect_b32 s43, s27, s62
	s_cselect_b32 s42, s60, s61
	v_lshl_add_u64 v[216:217], s[40:41], 0, v[136:137]
	s_add_i32 m0, s39, 0xc000
	ds_read_b128 v[184:187], v157
	ds_read_b128 v[188:191], v157 offset:1024
	ds_read_b128 v[192:195], v157 offset:2048
	ds_read_b128 v[196:199], v157 offset:3072
	ds_read_b128 v[200:203], v157 offset:4096
	ds_read_b128 v[204:207], v157 offset:5120
	ds_read_b128 v[208:211], v157 offset:6144
	ds_read_b128 v[212:215], v157 offset:7168
	global_load_lds_dwordx4 v[216:217], off
	v_lshl_add_u64 v[216:217], s[40:41], 0, v[138:139]
	s_add_i32 m0, s39, 0xe000
	s_nop 0
	global_load_lds_dwordx4 v[216:217], off
	s_waitcnt vmcnt(8)
	s_waitcnt lgkmcnt(0)
	s_setprio 1
	s_barrier
	v_mfma_f32_16x16x32_bf16 v[120:123], v[144:147], v[184:187], v[120:123]
	v_mfma_f32_16x16x32_bf16 v[124:127], v[160:163], v[184:187], v[124:127]
	v_mfma_f32_16x16x32_bf16 v[104:107], v[144:147], v[192:195], v[104:107]
	v_mfma_f32_16x16x32_bf16 v[108:111], v[160:163], v[192:195], v[108:111]
	v_mfma_f32_16x16x32_bf16 v[88:91], v[144:147], v[200:203], v[88:91]
	v_mfma_f32_16x16x32_bf16 v[92:95], v[160:163], v[200:203], v[92:95]
	v_mfma_f32_16x16x32_bf16 v[72:75], v[144:147], v[208:211], v[72:75]
	v_mfma_f32_16x16x32_bf16 v[76:79], v[160:163], v[208:211], v[76:79]
	v_mfma_f32_16x16x32_bf16 v[120:123], v[148:151], v[188:191], v[120:123]
	v_mfma_f32_16x16x32_bf16 v[124:127], v[164:167], v[188:191], v[124:127]
	v_mfma_f32_16x16x32_bf16 v[104:107], v[148:151], v[196:199], v[104:107]
	v_mfma_f32_16x16x32_bf16 v[108:111], v[164:167], v[196:199], v[108:111]
	v_mfma_f32_16x16x32_bf16 v[88:91], v[148:151], v[204:207], v[88:91]
	v_mfma_f32_16x16x32_bf16 v[92:95], v[164:167], v[204:207], v[92:95]
	v_mfma_f32_16x16x32_bf16 v[72:75], v[148:151], v[212:215], v[72:75]
	v_mfma_f32_16x16x32_bf16 v[76:79], v[164:167], v[212:215], v[76:79]
	s_setprio 0
	s_setprio 1
	v_mfma_f32_16x16x32_bf16 v[116:119], v[168:171], v[184:187], v[116:119]
	v_mfma_f32_16x16x32_bf16 v[112:115], v[176:179], v[184:187], v[112:115]
	v_mfma_f32_16x16x32_bf16 v[100:103], v[168:171], v[192:195], v[100:103]
	v_mfma_f32_16x16x32_bf16 v[96:99], v[176:179], v[192:195], v[96:99]
	v_mfma_f32_16x16x32_bf16 v[84:87], v[168:171], v[200:203], v[84:87]
	v_mfma_f32_16x16x32_bf16 v[80:83], v[176:179], v[200:203], v[80:83]
	v_mfma_f32_16x16x32_bf16 v[68:71], v[168:171], v[208:211], v[68:71]
	v_mfma_f32_16x16x32_bf16 v[64:67], v[176:179], v[208:211], v[64:67]
	v_mfma_f32_16x16x32_bf16 v[116:119], v[172:175], v[188:191], v[116:119]
	v_mfma_f32_16x16x32_bf16 v[112:115], v[180:183], v[188:191], v[112:115]
	v_mfma_f32_16x16x32_bf16 v[100:103], v[172:175], v[196:199], v[100:103]
	v_mfma_f32_16x16x32_bf16 v[96:99], v[180:183], v[196:199], v[96:99]
	v_mfma_f32_16x16x32_bf16 v[84:87], v[172:175], v[204:207], v[84:87]
	v_mfma_f32_16x16x32_bf16 v[80:83], v[180:183], v[204:207], v[80:83]
	v_mfma_f32_16x16x32_bf16 v[68:71], v[172:175], v[212:215], v[68:71]
	v_mfma_f32_16x16x32_bf16 v[64:67], v[180:183], v[212:215], v[64:67]
	s_setprio 0
	s_barrier
	s_add_i32 s64, s56, s48
	v_lshl_add_u64 v[216:217], s[42:43], 0, v[130:131]
	s_mov_b32 m0, s64
	ds_read_b128 v[184:187], v157 offset:16384
	ds_read_b128 v[188:191], v157 offset:17408
	ds_read_b128 v[192:195], v157 offset:18432
	ds_read_b128 v[196:199], v157 offset:19456
	ds_read_b128 v[200:203], v157 offset:20480
	ds_read_b128 v[204:207], v157 offset:21504
	ds_read_b128 v[208:211], v157 offset:22528
	ds_read_b128 v[212:215], v157 offset:23552
	global_load_lds_dwordx4 v[216:217], off
	s_add_i32 m0, s64, 0x2000
	s_add_u32 s64, s42, 0x100000
	v_lshl_add_u64 v[218:219], s[42:43], 0, v[134:135]
	s_addc_u32 s65, s43, 0
	s_add_i32 s66, s57, s48
	global_load_lds_dwordx4 v[218:219], off
	v_lshl_add_u64 v[220:221], s[64:65], 0, v[130:131]
	s_mov_b32 m0, s66
	v_lshl_add_u64 v[222:223], s[44:45], 0, v[132:133]
	global_load_lds_dwordx4 v[220:221], off
	v_lshl_add_u64 v[220:221], s[64:65], 0, v[134:135]
	s_add_i32 m0, s66, 0x2000
	s_nop 0
	global_load_lds_dwordx4 v[220:221], off
	v_lshl_add_u64 v[220:221], s[44:45], 0, v[128:129]
	s_mov_b32 m0, s39
	s_nop 0
	global_load_lds_dwordx4 v[220:221], off
	s_mov_b32 m0, s49
	s_nop 0
	global_load_lds_dwordx4 v[222:223], off
	s_waitcnt vmcnt(8)
	s_waitcnt lgkmcnt(0)
	s_setprio 1
	s_barrier
	v_mfma_f32_16x16x32_bf16 v[56:59], v[144:147], v[184:187], v[56:59]
	v_mfma_f32_16x16x32_bf16 v[60:63], v[160:163], v[184:187], v[60:63]
	v_mfma_f32_16x16x32_bf16 v[40:43], v[144:147], v[192:195], v[40:43]
	v_mfma_f32_16x16x32_bf16 v[44:47], v[160:163], v[192:195], v[44:47]
	v_mfma_f32_16x16x32_bf16 v[24:27], v[144:147], v[200:203], v[24:27]
	v_mfma_f32_16x16x32_bf16 v[28:31], v[160:163], v[200:203], v[28:31]
	v_mfma_f32_16x16x32_bf16 v[8:11], v[144:147], v[208:211], v[8:11]
	v_mfma_f32_16x16x32_bf16 v[12:15], v[160:163], v[208:211], v[12:15]
	v_mfma_f32_16x16x32_bf16 v[56:59], v[148:151], v[188:191], v[56:59]
	v_mfma_f32_16x16x32_bf16 v[60:63], v[164:167], v[188:191], v[60:63]
	v_mfma_f32_16x16x32_bf16 v[40:43], v[148:151], v[196:199], v[40:43]
	v_mfma_f32_16x16x32_bf16 v[44:47], v[164:167], v[196:199], v[44:47]
	v_mfma_f32_16x16x32_bf16 v[24:27], v[148:151], v[204:207], v[24:27]
	v_mfma_f32_16x16x32_bf16 v[28:31], v[164:167], v[204:207], v[28:31]
	v_mfma_f32_16x16x32_bf16 v[8:11], v[148:151], v[212:215], v[8:11]
	v_mfma_f32_16x16x32_bf16 v[12:15], v[164:167], v[212:215], v[12:15]
	s_setprio 0
	s_setprio 1
	v_mfma_f32_16x16x32_bf16 v[52:55], v[168:171], v[184:187], v[52:55]
	v_mfma_f32_16x16x32_bf16 v[48:51], v[176:179], v[184:187], v[48:51]
	v_mfma_f32_16x16x32_bf16 v[36:39], v[168:171], v[192:195], v[36:39]
	v_mfma_f32_16x16x32_bf16 v[32:35], v[176:179], v[192:195], v[32:35]
	v_mfma_f32_16x16x32_bf16 v[20:23], v[168:171], v[200:203], v[20:23]
	v_mfma_f32_16x16x32_bf16 v[16:19], v[176:179], v[200:203], v[16:19]
	v_mfma_f32_16x16x32_bf16 v[4:7], v[168:171], v[208:211], v[4:7]
	v_mfma_f32_16x16x32_bf16 v[0:3], v[176:179], v[208:211], v[0:3]
	v_mfma_f32_16x16x32_bf16 v[52:55], v[172:175], v[188:191], v[52:55]
	v_mfma_f32_16x16x32_bf16 v[48:51], v[180:183], v[188:191], v[48:51]
	v_mfma_f32_16x16x32_bf16 v[36:39], v[172:175], v[196:199], v[36:39]
	v_mfma_f32_16x16x32_bf16 v[32:35], v[180:183], v[196:199], v[32:35]
	v_mfma_f32_16x16x32_bf16 v[20:23], v[172:175], v[204:207], v[20:23]
	v_mfma_f32_16x16x32_bf16 v[16:19], v[180:183], v[204:207], v[16:19]
	v_mfma_f32_16x16x32_bf16 v[4:7], v[172:175], v[212:215], v[4:7]
	v_mfma_f32_16x16x32_bf16 v[0:3], v[180:183], v[212:215], v[0:3]
	s_setprio 0
	s_barrier
	s_add_i32 s64, 0, 0x18000
	v_add_u32_e32 v159, s64, v153
	s_add_i32 s65, 0, 0x1c000
	ds_read_b128 v[144:147], v159
	ds_read_b128 v[148:151], v159 offset:1024
	ds_read_b128 v[160:163], v159 offset:2048
	ds_read_b128 v[164:167], v159 offset:3072
	v_add_u32_e32 v159, s65, v153
	ds_read_b128 v[168:171], v159
	ds_read_b128 v[172:175], v159 offset:1024
	ds_read_b128 v[176:179], v159 offset:2048
	ds_read_b128 v[180:183], v159 offset:3072
	s_add_u32 s44, s44, 0x100000
	s_addc_u32 s45, s45, 0
	s_mov_b32 m0, s50
	v_lshl_add_u64 v[224:225], s[44:45], 0, v[128:129]
	ds_read_b128 v[184:187], v157 offset:32768
	ds_read_b128 v[188:191], v157 offset:33792
	ds_read_b128 v[192:195], v157 offset:34816
	ds_read_b128 v[196:199], v157 offset:35840
	ds_read_b128 v[200:203], v157 offset:36864
	ds_read_b128 v[204:207], v157 offset:37888
	ds_read_b128 v[208:211], v157 offset:38912
	ds_read_b128 v[212:215], v157 offset:39936
	global_load_lds_dwordx4 v[224:225], off
	v_lshl_add_u64 v[224:225], s[44:45], 0, v[132:133]
	s_mov_b32 m0, s51
	s_nop 0
	global_load_lds_dwordx4 v[224:225], off
	s_waitcnt vmcnt(8)
	s_waitcnt lgkmcnt(0)
	s_setprio 1
	s_barrier
	v_mfma_f32_16x16x32_bf16 v[120:123], v[144:147], v[184:187], v[120:123]
	v_mfma_f32_16x16x32_bf16 v[124:127], v[160:163], v[184:187], v[124:127]
	v_mfma_f32_16x16x32_bf16 v[104:107], v[144:147], v[192:195], v[104:107]
	v_mfma_f32_16x16x32_bf16 v[108:111], v[160:163], v[192:195], v[108:111]
	v_mfma_f32_16x16x32_bf16 v[88:91], v[144:147], v[200:203], v[88:91]
	v_mfma_f32_16x16x32_bf16 v[92:95], v[160:163], v[200:203], v[92:95]
	v_mfma_f32_16x16x32_bf16 v[72:75], v[144:147], v[208:211], v[72:75]
	v_mfma_f32_16x16x32_bf16 v[76:79], v[160:163], v[208:211], v[76:79]
	v_mfma_f32_16x16x32_bf16 v[120:123], v[148:151], v[188:191], v[120:123]
	v_mfma_f32_16x16x32_bf16 v[124:127], v[164:167], v[188:191], v[124:127]
	v_mfma_f32_16x16x32_bf16 v[104:107], v[148:151], v[196:199], v[104:107]
	v_mfma_f32_16x16x32_bf16 v[108:111], v[164:167], v[196:199], v[108:111]
	v_mfma_f32_16x16x32_bf16 v[88:91], v[148:151], v[204:207], v[88:91]
	v_mfma_f32_16x16x32_bf16 v[92:95], v[164:167], v[204:207], v[92:95]
	v_mfma_f32_16x16x32_bf16 v[72:75], v[148:151], v[212:215], v[72:75]
	v_mfma_f32_16x16x32_bf16 v[76:79], v[164:167], v[212:215], v[76:79]
	s_setprio 0
	s_setprio 1
	v_mfma_f32_16x16x32_bf16 v[116:119], v[168:171], v[184:187], v[116:119]
	v_mfma_f32_16x16x32_bf16 v[112:115], v[176:179], v[184:187], v[112:115]
	v_mfma_f32_16x16x32_bf16 v[100:103], v[168:171], v[192:195], v[100:103]
	v_mfma_f32_16x16x32_bf16 v[96:99], v[176:179], v[192:195], v[96:99]
	v_mfma_f32_16x16x32_bf16 v[84:87], v[168:171], v[200:203], v[84:87]
	v_mfma_f32_16x16x32_bf16 v[80:83], v[176:179], v[200:203], v[80:83]
	v_mfma_f32_16x16x32_bf16 v[68:71], v[168:171], v[208:211], v[68:71]
	v_mfma_f32_16x16x32_bf16 v[64:67], v[176:179], v[208:211], v[64:67]
	v_mfma_f32_16x16x32_bf16 v[116:119], v[172:175], v[188:191], v[116:119]
	v_mfma_f32_16x16x32_bf16 v[112:115], v[180:183], v[188:191], v[112:115]
	v_mfma_f32_16x16x32_bf16 v[100:103], v[172:175], v[196:199], v[100:103]
	v_mfma_f32_16x16x32_bf16 v[96:99], v[180:183], v[196:199], v[96:99]
	v_mfma_f32_16x16x32_bf16 v[84:87], v[172:175], v[204:207], v[84:87]
	v_mfma_f32_16x16x32_bf16 v[80:83], v[180:183], v[204:207], v[80:83]
	v_mfma_f32_16x16x32_bf16 v[68:71], v[172:175], v[212:215], v[68:71]
	v_mfma_f32_16x16x32_bf16 v[64:67], v[180:183], v[212:215], v[64:67]
	s_setprio 0
	s_barrier
	s_add_i32 s44, s64, s48
	v_lshl_add_u64 v[216:217], v[216:217], 0, s[12:13]
	s_mov_b32 m0, s44
	ds_read_b128 v[184:187], v157 offset:49152
	ds_read_b128 v[188:191], v157 offset:50176
	ds_read_b128 v[192:195], v157 offset:51200
	ds_read_b128 v[196:199], v157 offset:52224
	ds_read_b128 v[200:203], v157 offset:53248
	ds_read_b128 v[204:207], v157 offset:54272
	ds_read_b128 v[208:211], v157 offset:55296
	ds_read_b128 v[212:215], v157 offset:56320
	global_load_lds_dwordx4 v[216:217], off
	s_add_i32 m0, s44, 0x2000
	s_add_u32 s42, s42, 0x100080
	v_lshl_add_u64 v[216:217], v[218:219], 0, s[12:13]
	s_addc_u32 s43, s43, 0
	s_add_i32 s44, s65, s48
	global_load_lds_dwordx4 v[216:217], off
	v_lshl_add_u64 v[216:217], s[42:43], 0, v[130:131]
	s_mov_b32 m0, s44
	s_nop 0
	global_load_lds_dwordx4 v[216:217], off
	v_lshl_add_u64 v[216:217], s[42:43], 0, v[134:135]
	s_add_i32 m0, s44, 0x2000
	s_nop 0
	global_load_lds_dwordx4 v[216:217], off
	v_lshl_add_u64 v[216:217], v[220:221], 0, s[12:13]
	s_mov_b32 m0, s53
	s_nop 0
	global_load_lds_dwordx4 v[216:217], off
	v_lshl_add_u64 v[216:217], v[222:223], 0, s[12:13]
	s_mov_b32 m0, s54
	s_nop 0
	global_load_lds_dwordx4 v[216:217], off
	s_waitcnt vmcnt(8)
	s_waitcnt lgkmcnt(0)
	s_setprio 1
	s_barrier
	v_mfma_f32_16x16x32_bf16 v[56:59], v[144:147], v[184:187], v[56:59]
	v_mfma_f32_16x16x32_bf16 v[60:63], v[160:163], v[184:187], v[60:63]
	v_mfma_f32_16x16x32_bf16 v[40:43], v[144:147], v[192:195], v[40:43]
	v_mfma_f32_16x16x32_bf16 v[44:47], v[160:163], v[192:195], v[44:47]
	v_mfma_f32_16x16x32_bf16 v[24:27], v[144:147], v[200:203], v[24:27]
	v_mfma_f32_16x16x32_bf16 v[28:31], v[160:163], v[200:203], v[28:31]
	v_mfma_f32_16x16x32_bf16 v[8:11], v[144:147], v[208:211], v[8:11]
	v_mfma_f32_16x16x32_bf16 v[12:15], v[160:163], v[208:211], v[12:15]
	v_mfma_f32_16x16x32_bf16 v[56:59], v[148:151], v[188:191], v[56:59]
	v_mfma_f32_16x16x32_bf16 v[60:63], v[164:167], v[188:191], v[60:63]
	v_mfma_f32_16x16x32_bf16 v[40:43], v[148:151], v[196:199], v[40:43]
	v_mfma_f32_16x16x32_bf16 v[44:47], v[164:167], v[196:199], v[44:47]
	v_mfma_f32_16x16x32_bf16 v[24:27], v[148:151], v[204:207], v[24:27]
	v_mfma_f32_16x16x32_bf16 v[28:31], v[164:167], v[204:207], v[28:31]
	v_mfma_f32_16x16x32_bf16 v[8:11], v[148:151], v[212:215], v[8:11]
	v_mfma_f32_16x16x32_bf16 v[12:15], v[164:167], v[212:215], v[12:15]
	s_setprio 0
	s_setprio 1
	v_mfma_f32_16x16x32_bf16 v[52:55], v[168:171], v[184:187], v[52:55]
	v_mfma_f32_16x16x32_bf16 v[48:51], v[176:179], v[184:187], v[48:51]
	v_mfma_f32_16x16x32_bf16 v[36:39], v[168:171], v[192:195], v[36:39]
	v_mfma_f32_16x16x32_bf16 v[32:35], v[176:179], v[192:195], v[32:35]
	v_mfma_f32_16x16x32_bf16 v[20:23], v[168:171], v[200:203], v[20:23]
	v_mfma_f32_16x16x32_bf16 v[16:19], v[176:179], v[200:203], v[16:19]
	v_mfma_f32_16x16x32_bf16 v[4:7], v[168:171], v[208:211], v[4:7]
	v_mfma_f32_16x16x32_bf16 v[0:3], v[176:179], v[208:211], v[0:3]
	s_add_i32 s63, s63, 2
	s_add_u32 s40, s40, 0x100
	s_addc_u32 s41, s41, 0
	s_add_u32 s61, s61, 0x100
	s_addc_u32 s62, s62, 0
	s_cmp_gt_u32 s63, 61
	v_mfma_f32_16x16x32_bf16 v[52:55], v[172:175], v[188:191], v[52:55]
	v_mfma_f32_16x16x32_bf16 v[48:51], v[180:183], v[188:191], v[48:51]
	v_mfma_f32_16x16x32_bf16 v[36:39], v[172:175], v[196:199], v[36:39]
	v_mfma_f32_16x16x32_bf16 v[32:35], v[180:183], v[196:199], v[32:35]
	v_mfma_f32_16x16x32_bf16 v[20:23], v[172:175], v[204:207], v[20:23]
	v_mfma_f32_16x16x32_bf16 v[16:19], v[180:183], v[204:207], v[16:19]
	v_mfma_f32_16x16x32_bf16 v[4:7], v[172:175], v[212:215], v[4:7]
	v_mfma_f32_16x16x32_bf16 v[0:3], v[180:183], v[212:215], v[0:3]
	s_setprio 0
	s_barrier
	s_cbranch_scc0 .LBB0_1402
	s_and_b64 vcc, exec, s[16:17]
	s_cbranch_vccz .LBB0_1405
	s_barrier
